# v7: sample rows of the five N=1024 residual GEMMs computed by a hand-written split-K mini GEMM on all CUs (no 4-CU second round); bf16 MFMA f32 acc as before
# speedup vs baseline: 1.1043x; 1.0675x over previous
.Lcpya_loop:
	s_add_i32 s101, s80, s100
	s_cmp_lt_u32 s101, 0x1f40
	s_cbranch_scc0 .Lcpya_tail
	s_mul_hi_u32 s81, s80, 0x2ad5802b
	s_lshr_b32 s81, s81, 8
	s_mul_i32 s82, s81, 0x5fa
	s_sub_i32 s82, s80, s82
	s_lshl_b32 s82, s82, 13
	s_and_b32 s83, s81, 31
	s_mul_i32 s83, s83, 0xc00000
	s_add_i32 s82, s82, s83
	s_cmp_lt_u32 s81, 32
	s_cselect_b32 s84, s92, s94
	s_cselect_b32 s85, s93, s95
	s_mov_b32 s83, 0x1f210000
	s_cselect_b32 s83, 0x7210000, s83
	s_add_u32 s84, s84, s82
	s_addc_u32 s85, s85, 0
	s_add_u32 s84, s84, 0xc000
	s_addc_u32 s85, s85, 0
	s_add_u32 s83, s83, s82
	s_add_u32 s86, s98, s83
	s_addc_u32 s87, s99, 0
	s_mul_hi_u32 s81, s101, 0x2ad5802b
	s_lshr_b32 s81, s81, 8
	s_mul_i32 s82, s81, 0x5fa
	s_sub_i32 s82, s101, s82
	s_lshl_b32 s82, s82, 13
	s_and_b32 s83, s81, 31
	s_mul_i32 s83, s83, 0xc00000
	s_add_i32 s82, s82, s83
	s_cmp_lt_u32 s81, 32
	s_cselect_b32 s88, s92, s94
	s_cselect_b32 s89, s93, s95
	s_mov_b32 s83, 0x1f210000
	s_cselect_b32 s83, 0x7210000, s83
	s_add_u32 s88, s88, s82
	s_addc_u32 s89, s89, 0
	s_add_u32 s88, s88, 0xc000
	s_addc_u32 s89, s89, 0
	s_add_u32 s83, s83, s82
	s_add_u32 s90, s98, s83
	s_addc_u32 s91, s99, 0
	global_load_dwordx4 v[64:67], v22, s[84:85] nt
	global_load_dwordx4 v[68:71], v22, s[84:85] offset:1024 nt
	global_load_dwordx4 v[72:75], v22, s[84:85] offset:2048 nt
	global_load_dwordx4 v[76:79], v22, s[84:85] offset:3072 nt
	global_load_dwordx4 v[80:83], v23, s[84:85] nt
	global_load_dwordx4 v[84:87], v23, s[84:85] offset:1024 nt
	global_load_dwordx4 v[88:91], v23, s[84:85] offset:2048 nt
	global_load_dwordx4 v[92:95], v23, s[84:85] offset:3072 nt
	global_load_dwordx4 v[96:99], v22, s[88:89] nt
	global_load_dwordx4 v[100:103], v22, s[88:89] offset:1024 nt
	global_load_dwordx4 v[104:107], v22, s[88:89] offset:2048 nt
	global_load_dwordx4 v[108:111], v22, s[88:89] offset:3072 nt
	global_load_dwordx4 v[112:115], v23, s[88:89] nt
	global_load_dwordx4 v[116:119], v23, s[88:89] offset:1024 nt
	global_load_dwordx4 v[120:123], v23, s[88:89] offset:2048 nt
	global_load_dwordx4 v[124:127], v23, s[88:89] offset:3072 nt
	s_waitcnt vmcnt(15)
	global_store_dwordx4 v22, v[64:67], s[86:87] nt
	s_waitcnt vmcnt(15)
	global_store_dwordx4 v22, v[68:71], s[86:87] offset:1024 nt
	s_waitcnt vmcnt(15)
	global_store_dwordx4 v22, v[72:75], s[86:87] offset:2048 nt
	s_waitcnt vmcnt(15)
	global_store_dwordx4 v22, v[76:79], s[86:87] offset:3072 nt
	s_waitcnt vmcnt(15)
	global_store_dwordx4 v23, v[80:83], s[86:87] nt
	s_waitcnt vmcnt(15)
	global_store_dwordx4 v23, v[84:87], s[86:87] offset:1024 nt
	s_waitcnt vmcnt(15)
	global_store_dwordx4 v23, v[88:91], s[86:87] offset:2048 nt
	s_waitcnt vmcnt(15)
	global_store_dwordx4 v23, v[92:95], s[86:87] offset:3072 nt
	s_waitcnt vmcnt(15)
	global_store_dwordx4 v22, v[96:99], s[90:91] nt
	s_waitcnt vmcnt(15)
	global_store_dwordx4 v22, v[100:103], s[90:91] offset:1024 nt
	s_waitcnt vmcnt(15)
	global_store_dwordx4 v22, v[104:107], s[90:91] offset:2048 nt
	s_waitcnt vmcnt(15)
	global_store_dwordx4 v22, v[108:111], s[90:91] offset:3072 nt
	s_waitcnt vmcnt(15)
	global_store_dwordx4 v23, v[112:115], s[90:91] nt
	s_waitcnt vmcnt(15)
	global_store_dwordx4 v23, v[116:119], s[90:91] offset:1024 nt
	s_waitcnt vmcnt(15)
	global_store_dwordx4 v23, v[120:123], s[90:91] offset:2048 nt
	s_waitcnt vmcnt(15)
	global_store_dwordx4 v23, v[124:127], s[90:91] offset:3072 nt
	s_add_i32 s80, s101, s100
	s_branch .Lcpya_loop
.Lcpya_tail:
	s_cmp_lt_u32 s80, 0x1f40
	s_cbranch_scc0 .Lcpya_end
	s_mul_hi_u32 s81, s80, 0x2ad5802b
	s_lshr_b32 s81, s81, 8
	s_mul_i32 s82, s81, 0x5fa
	s_sub_i32 s82, s80, s82
	s_lshl_b32 s82, s82, 13
	s_and_b32 s83, s81, 31
	s_mul_i32 s83, s83, 0xc00000
	s_add_i32 s82, s82, s83
	s_cmp_lt_u32 s81, 32
	s_cselect_b32 s84, s92, s94
	s_cselect_b32 s85, s93, s95
	s_mov_b32 s83, 0x1f210000
	s_cselect_b32 s83, 0x7210000, s83
	s_add_u32 s84, s84, s82
	s_addc_u32 s85, s85, 0
	s_add_u32 s84, s84, 0xc000
	s_addc_u32 s85, s85, 0
	s_add_u32 s83, s83, s82
	s_add_u32 s86, s98, s83
	s_addc_u32 s87, s99, 0
	global_load_dwordx4 v[64:67], v22, s[84:85] nt
	global_load_dwordx4 v[68:71], v22, s[84:85] offset:1024 nt
	global_load_dwordx4 v[72:75], v22, s[84:85] offset:2048 nt
	global_load_dwordx4 v[76:79], v22, s[84:85] offset:3072 nt
	global_load_dwordx4 v[80:83], v23, s[84:85] nt
	global_load_dwordx4 v[84:87], v23, s[84:85] offset:1024 nt
	global_load_dwordx4 v[88:91], v23, s[84:85] offset:2048 nt
	global_load_dwordx4 v[92:95], v23, s[84:85] offset:3072 nt
	s_waitcnt vmcnt(7)
	global_store_dwordx4 v22, v[64:67], s[86:87] nt
	s_waitcnt vmcnt(7)
	global_store_dwordx4 v22, v[68:71], s[86:87] offset:1024 nt
	s_waitcnt vmcnt(7)
	global_store_dwordx4 v22, v[72:75], s[86:87] offset:2048 nt
	s_waitcnt vmcnt(7)
	global_store_dwordx4 v22, v[76:79], s[86:87] offset:3072 nt
	s_waitcnt vmcnt(7)
	global_store_dwordx4 v23, v[80:83], s[86:87] nt
	s_waitcnt vmcnt(7)
	global_store_dwordx4 v23, v[84:87], s[86:87] offset:1024 nt
	s_waitcnt vmcnt(7)
	global_store_dwordx4 v23, v[88:91], s[86:87] offset:2048 nt
	s_waitcnt vmcnt(7)
	global_store_dwordx4 v23, v[92:95], s[86:87] offset:3072 nt

.LBB0_221:
	s_or_b64 exec, exec, s[4:5]
	v_mov_b32_e32 v8, v174
	s_cmpk_lt_i32 s2, 0x104
	s_barrier
	s_cselect_b64 s[6:7], -1, 0
	s_cmpk_gt_i32 s2, 0x103
	v_readfirstlane_b32 s46, v8
	s_cbranch_scc1 .LBB0_227
	s_ashr_i32 s4, s2, 31
	s_lshr_b32 s4, s4, 29
	s_add_i32 s8, s2, s4
	s_and_b32 s4, s8, -8
	s_sub_i32 s9, s2, s4
	s_cmp_gt_i32 s9, -1
	s_cbranch_scc0 .LBB0_224
	s_lshl_b32 s4, s9, 5
	s_or_b32 s10, s4, 0
	s_cbranch_execz .LBB0_225
	s_branch .LBB0_226

.LBB0_230:
	s_lshl_b32 s7, s7, 5
	s_mov_b64 s[24:25], 0x80
	s_and_b32 s12, s7, 0x60
	s_add_i32 m0, s52, 0x18000
	v_lshl_add_u64 v[6:7], v[6:7], 0, s[24:25]
	s_lshl_b32 s9, s6, 13
	s_lshl_b32 s7, s12, 7
	s_waitcnt vmcnt(4)
	s_barrier
	global_load_lds_dwordx4 v[6:7], off
	v_lshl_add_u64 v[4:5], v[4:5], 0, s[24:25]
	s_add_i32 m0, s52, 0x1a000
	s_add_i32 s57, s52, 0x8000
	s_add_i32 s62, s52, 0xa000
	global_load_lds_dwordx4 v[4:5], off
	v_lshl_add_u64 v[2:3], v[2:3], 0, s[24:25]
	s_mov_b32 m0, s57
	s_add_u32 s10, s30, 0xb0080
	global_load_lds_dwordx4 v[2:3], off
	v_lshl_add_u64 v[0:1], v[0:1], 0, s[24:25]
	s_mov_b32 m0, s62
	s_addc_u32 s11, s31, 0
	global_load_lds_dwordx4 v[0:1], off
	s_add_i32 m0, s52, 0x1c000
	v_lshl_add_u64 v[0:1], s[10:11], 0, v[130:131]
	global_load_lds_dwordx4 v[0:1], off
	v_lshl_add_u64 v[0:1], s[10:11], 0, v[134:135]
	s_add_i32 m0, s52, 0x1e000
	s_mov_b64 s[10:11], 0xb0080
	global_load_lds_dwordx4 v[0:1], off
	v_bfe_u32 v0, v8, 4, 2
	v_and_b32_e32 v1, 15, v8
	v_lshlrev_b32_e32 v2, 4, v0
	v_lshl_or_b32 v148, s6, 6, v1
	v_lshl_or_b32 v1, v1, 6, v2
	v_lshlrev_b32_e32 v2, 2, v8
	v_and_b32_e32 v2, 32, v2
	v_bitop3_b32 v3, v1, s9, v2 bitop3:0xde
	v_bitop3_b32 v149, v1, s7, v2 bitop3:0xde
	v_cmp_eq_u32_e64 s[6:7], 0, v0
	v_lshl_or_b32 v150, v0, 3, s12
	v_lshrrev_b32_e32 v1, 1, v9
	v_mul_lo_u32 v0, v11, s8
	s_mov_b32 s9, 0xb000
	v_mad_u64_u32 v[0:1], s[12:13], v1, s9, v[0:1]
	v_or_b32_e32 v0, v0, v10
	v_add_lshl_u32 v0, v0, v12, 1
	v_mov_b32_e32 v1, v131
	v_lshl_add_u64 v[136:137], v[0:1], 0, s[10:11]
	v_lshrrev_b32_e32 v1, 1, v13
	v_mul_lo_u32 v0, v14, s8
	v_mad_u64_u32 v[0:1], s[8:9], v1, s9, v[0:1]
	s_waitcnt vmcnt(6)
	v_or_b32_e32 v0, v0, v15
	v_add_lshl_u32 v0, v0, v16, 1
	v_mov_b32_e32 v1, v131
	s_add_i32 s65, 0, 0x10000
	s_add_i32 s66, 0, 0x14000
	s_bfe_i64 s[26:27], s[78:79], 0x200000
	s_ashr_i32 s63, s2, 31
	s_mov_b32 s64, s2
	v_lshl_add_u64 v[138:139], v[0:1], 0, s[10:11]
	v_mov_b64_e32 v[140:141], 0x100
	v_mov_b64_e32 v[142:143], 0xff
	v_add_u32_e32 v151, s65, v149
	v_add_u32_e32 v152, 0, v3
	v_add_u32_e32 v153, s66, v149
	v_mbcnt_hi_u32_b32 v154, -1, v175
	s_barrier
	s_branch .LBB0_232

.LBB0_263:
	v_and_b32_e32 v160, 15, v174
	v_bfe_u32 v161, v174, 4, 2
	v_lshrrev_b32_e32 v162, 6, v174
	v_and_b32_e32 v136, 63, v174
	v_readfirstlane_b32 s80, v162
	s_lshr_b32 s81, s33, 8
	s_lshr_b32 s82, s33, 3
	s_and_b32 s82, s82, 31
	s_mul_i32 s83, s80, 704
	v_lshlrev_b32_e32 v164, 4, v161
	v_mov_b32_e32 v167, 0
	s_lshl_b32 s84, s82, 5
	v_add_u32_e32 v165, s84, v160
	v_mul_u32_u24_e32 v166, 0x1600, v165
	v_add3_u32 v166, v166, v164, s83
	s_add_u32 s86, s74, 0x2c00000
	s_addc_u32 s87, s75, 0
	s_mov_b32 s88, 0x16000
	s_mov_b32 s89, 0
	v_lshl_add_u64 v[152:153], s[86:87], 0, v[166:167]
	v_lshl_add_u64 v[154:155], v[152:153], 0, s[88:89]
	s_lshl_b32 s84, s81, 5
	v_add_u32_e32 v165, s84, v160
	v_mul_u32_u24_e32 v166, 0x1600, v165
	v_add3_u32 v166, v166, v164, s83
	s_add_u32 s90, s74, 0x10980000
	s_addc_u32 s91, s75, 0
	v_lshl_add_u64 v[156:157], s[90:91], 0, v[166:167]
	v_lshl_add_u64 v[158:159], v[156:157], 0, s[88:89]
	v_mov_b32_e32 v128, 0
	v_mov_b32_e32 v129, 0
	v_mov_b32_e32 v130, 0
	v_mov_b32_e32 v131, 0
	v_mov_b32_e32 v132, 0
	v_mov_b32_e32 v133, 0
	v_mov_b32_e32 v134, 0
	v_mov_b32_e32 v135, 0
	v_mov_b32_e32 v144, 0
	v_mov_b32_e32 v145, 0
	v_mov_b32_e32 v146, 0
	v_mov_b32_e32 v147, 0
	v_mov_b32_e32 v148, 0
	v_mov_b32_e32 v149, 0
	v_mov_b32_e32 v150, 0
	v_mov_b32_e32 v151, 0
	global_load_dwordx4 v[0:3], v[152:153], off
	global_load_dwordx4 v[4:7], v[154:155], off
	global_load_dwordx4 v[8:11], v[156:157], off
	global_load_dwordx4 v[12:15], v[158:159], off
	global_load_dwordx4 v[16:19], v[152:153], off offset:64
	global_load_dwordx4 v[20:23], v[154:155], off offset:64
	global_load_dwordx4 v[24:27], v[156:157], off offset:64
	global_load_dwordx4 v[28:31], v[158:159], off offset:64
	global_load_dwordx4 v[32:35], v[152:153], off offset:128
	global_load_dwordx4 v[36:39], v[154:155], off offset:128
	global_load_dwordx4 v[40:43], v[156:157], off offset:128
	global_load_dwordx4 v[44:47], v[158:159], off offset:128
	global_load_dwordx4 v[48:51], v[152:153], off offset:192
	global_load_dwordx4 v[52:55], v[154:155], off offset:192
	global_load_dwordx4 v[56:59], v[156:157], off offset:192
	global_load_dwordx4 v[60:63], v[158:159], off offset:192
	global_load_dwordx4 v[64:67], v[152:153], off offset:256
	global_load_dwordx4 v[68:71], v[154:155], off offset:256
	global_load_dwordx4 v[72:75], v[156:157], off offset:256
	global_load_dwordx4 v[76:79], v[158:159], off offset:256
	global_load_dwordx4 v[80:83], v[152:153], off offset:320
	global_load_dwordx4 v[84:87], v[154:155], off offset:320
	global_load_dwordx4 v[88:91], v[156:157], off offset:320
	global_load_dwordx4 v[92:95], v[158:159], off offset:320
	global_load_dwordx4 v[96:99], v[152:153], off offset:384
	global_load_dwordx4 v[100:103], v[154:155], off offset:384
	global_load_dwordx4 v[104:107], v[156:157], off offset:384
	global_load_dwordx4 v[108:111], v[158:159], off offset:384
	global_load_dwordx4 v[112:115], v[152:153], off offset:448
	global_load_dwordx4 v[116:119], v[154:155], off offset:448
	global_load_dwordx4 v[120:123], v[156:157], off offset:448
	global_load_dwordx4 v[124:127], v[158:159], off offset:448
	s_waitcnt vmcnt(16)
	v_mfma_f32_16x16x32_bf16 v[128:131], v[0:3], v[8:11], v[128:131]
	v_mfma_f32_16x16x32_bf16 v[132:135], v[4:7], v[8:11], v[132:135]
	v_mfma_f32_16x16x32_bf16 v[144:147], v[0:3], v[12:15], v[144:147]
	v_mfma_f32_16x16x32_bf16 v[148:151], v[4:7], v[12:15], v[148:151]
	v_mfma_f32_16x16x32_bf16 v[128:131], v[16:19], v[24:27], v[128:131]
	v_mfma_f32_16x16x32_bf16 v[132:135], v[20:23], v[24:27], v[132:135]
	v_mfma_f32_16x16x32_bf16 v[144:147], v[16:19], v[28:31], v[144:147]
	v_mfma_f32_16x16x32_bf16 v[148:151], v[20:23], v[28:31], v[148:151]
	v_mfma_f32_16x16x32_bf16 v[128:131], v[32:35], v[40:43], v[128:131]
	v_mfma_f32_16x16x32_bf16 v[132:135], v[36:39], v[40:43], v[132:135]
	v_mfma_f32_16x16x32_bf16 v[144:147], v[32:35], v[44:47], v[144:147]
	v_mfma_f32_16x16x32_bf16 v[148:151], v[36:39], v[44:47], v[148:151]
	v_mfma_f32_16x16x32_bf16 v[128:131], v[48:51], v[56:59], v[128:131]
	v_mfma_f32_16x16x32_bf16 v[132:135], v[52:55], v[56:59], v[132:135]
	v_mfma_f32_16x16x32_bf16 v[144:147], v[48:51], v[60:63], v[144:147]
	v_mfma_f32_16x16x32_bf16 v[148:151], v[52:55], v[60:63], v[148:151]
	global_load_dwordx4 v[0:3], v[152:153], off offset:512
	global_load_dwordx4 v[4:7], v[154:155], off offset:512
	global_load_dwordx4 v[8:11], v[156:157], off offset:512
	global_load_dwordx4 v[12:15], v[158:159], off offset:512
	global_load_dwordx4 v[16:19], v[152:153], off offset:576
	global_load_dwordx4 v[20:23], v[154:155], off offset:576
	global_load_dwordx4 v[24:27], v[156:157], off offset:576
	global_load_dwordx4 v[28:31], v[158:159], off offset:576
	global_load_dwordx4 v[32:35], v[152:153], off offset:640
	global_load_dwordx4 v[36:39], v[154:155], off offset:640
	global_load_dwordx4 v[40:43], v[156:157], off offset:640
	global_load_dwordx4 v[44:47], v[158:159], off offset:640
	s_waitcnt vmcnt(12)
	v_mfma_f32_16x16x32_bf16 v[128:131], v[64:67], v[72:75], v[128:131]
	v_mfma_f32_16x16x32_bf16 v[132:135], v[68:71], v[72:75], v[132:135]
	v_mfma_f32_16x16x32_bf16 v[144:147], v[64:67], v[76:79], v[144:147]
	v_mfma_f32_16x16x32_bf16 v[148:151], v[68:71], v[76:79], v[148:151]
	v_mfma_f32_16x16x32_bf16 v[128:131], v[80:83], v[88:91], v[128:131]
	v_mfma_f32_16x16x32_bf16 v[132:135], v[84:87], v[88:91], v[132:135]
	v_mfma_f32_16x16x32_bf16 v[144:147], v[80:83], v[92:95], v[144:147]
	v_mfma_f32_16x16x32_bf16 v[148:151], v[84:87], v[92:95], v[148:151]
	v_mfma_f32_16x16x32_bf16 v[128:131], v[96:99], v[104:107], v[128:131]
	v_mfma_f32_16x16x32_bf16 v[132:135], v[100:103], v[104:107], v[132:135]
	v_mfma_f32_16x16x32_bf16 v[144:147], v[96:99], v[108:111], v[144:147]
	v_mfma_f32_16x16x32_bf16 v[148:151], v[100:103], v[108:111], v[148:151]
	v_mfma_f32_16x16x32_bf16 v[128:131], v[112:115], v[120:123], v[128:131]
	v_mfma_f32_16x16x32_bf16 v[132:135], v[116:119], v[120:123], v[132:135]
	v_mfma_f32_16x16x32_bf16 v[144:147], v[112:115], v[124:127], v[144:147]
	v_mfma_f32_16x16x32_bf16 v[148:151], v[116:119], v[124:127], v[148:151]
	s_waitcnt vmcnt(0)
	v_mfma_f32_16x16x32_bf16 v[128:131], v[0:3], v[8:11], v[128:131]
	v_mfma_f32_16x16x32_bf16 v[132:135], v[4:7], v[8:11], v[132:135]
	v_mfma_f32_16x16x32_bf16 v[144:147], v[0:3], v[12:15], v[144:147]
	v_mfma_f32_16x16x32_bf16 v[148:151], v[4:7], v[12:15], v[148:151]
	v_mfma_f32_16x16x32_bf16 v[128:131], v[16:19], v[24:27], v[128:131]
	v_mfma_f32_16x16x32_bf16 v[132:135], v[20:23], v[24:27], v[132:135]
	v_mfma_f32_16x16x32_bf16 v[144:147], v[16:19], v[28:31], v[144:147]
	v_mfma_f32_16x16x32_bf16 v[148:151], v[20:23], v[28:31], v[148:151]
	v_mfma_f32_16x16x32_bf16 v[128:131], v[32:35], v[40:43], v[128:131]
	v_mfma_f32_16x16x32_bf16 v[132:135], v[36:39], v[40:43], v[132:135]
	v_mfma_f32_16x16x32_bf16 v[144:147], v[32:35], v[44:47], v[144:147]
	v_mfma_f32_16x16x32_bf16 v[148:151], v[36:39], v[44:47], v[148:151]
	s_nop 7
	s_nop 7
	v_lshlrev_b32_e32 v170, 12, v162
	v_lshl_add_u32 v170, v136, 4, v170
	ds_write_b128 v170, v[128:131]
	ds_write_b128 v170, v[132:135] offset:1024
	ds_write_b128 v170, v[144:147] offset:2048
	ds_write_b128 v170, v[148:151] offset:3072
	s_waitcnt lgkmcnt(0)
	s_barrier
	s_cmp_ge_u32 s80, 4
	s_cbranch_scc1 .Lmg1_end
	s_lshl_b32 s84, s80, 10
	v_lshlrev_b32_e32 v171, 4, v136
	v_add_u32_e32 v171, s84, v171
	ds_read_b128 v[0:3], v171
	ds_read_b128 v[4:7], v171 offset:4096
	ds_read_b128 v[8:11], v171 offset:8192
	ds_read_b128 v[12:15], v171 offset:12288
	ds_read_b128 v[16:19], v171 offset:16384
	ds_read_b128 v[20:23], v171 offset:20480
	ds_read_b128 v[24:27], v171 offset:24576
	ds_read_b128 v[28:31], v171 offset:28672
	s_lshr_b32 s84, s80, 1
	s_lshl_b32 s84, s84, 4
	s_lshl_b32 s85, s81, 5
	s_add_i32 s84, s84, s85
	s_addk_i32 s84, 0x4000
	s_and_b32 s85, s80, 1
	s_lshl_b32 s85, s85, 4
	s_lshl_b32 s83, s82, 5
	s_add_i32 s85, s85, s83
	v_add_u32_e32 v165, s84, v160
	v_lshl_add_u32 v164, v161, 2, s85
	v_lshlrev_b32_e32 v166, 12, v165
	v_lshl_add_u32 v166, v164, 2, v166
	v_mov_b32_e32 v167, 0
	s_add_u32 s86, s74, 0x5000000
	s_addc_u32 s87, s75, 0
	v_lshl_add_u64 v[168:169], s[86:87], 0, v[166:167]
	global_load_dwordx4 v[32:35], v[168:169], off
	v_lshrrev_b32_e32 v172, 1, v166
	v_mov_b32_e32 v173, 0
	s_add_u32 s86, s74, 0x9100000
	s_addc_u32 s87, s75, 0
	v_lshl_add_u64 v[172:173], s[86:87], 0, v[172:173]
	v_lshlrev_b32_e32 v166, 2, v165
	s_add_u32 s86, s74, 0x12b70400
	s_addc_u32 s87, s75, 0
	v_lshl_add_u64 v[166:167], s[86:87], 0, v[166:167]
	s_waitcnt lgkmcnt(0)
	v_add_f32_e32 v0, v0, v4
	v_add_f32_e32 v1, v1, v5
	v_add_f32_e32 v2, v2, v6
	v_add_f32_e32 v3, v3, v7
	v_add_f32_e32 v0, v0, v8
	v_add_f32_e32 v1, v1, v9
	v_add_f32_e32 v2, v2, v10
	v_add_f32_e32 v3, v3, v11
	v_add_f32_e32 v0, v0, v12
	v_add_f32_e32 v1, v1, v13
	v_add_f32_e32 v2, v2, v14
	v_add_f32_e32 v3, v3, v15
	v_add_f32_e32 v0, v0, v16
	v_add_f32_e32 v1, v1, v17
	v_add_f32_e32 v2, v2, v18
	v_add_f32_e32 v3, v3, v19
	v_add_f32_e32 v0, v0, v20
	v_add_f32_e32 v1, v1, v21
	v_add_f32_e32 v2, v2, v22
	v_add_f32_e32 v3, v3, v23
	v_add_f32_e32 v0, v0, v24
	v_add_f32_e32 v1, v1, v25
	v_add_f32_e32 v2, v2, v26
	v_add_f32_e32 v3, v3, v27
	v_add_f32_e32 v0, v0, v28
	v_add_f32_e32 v1, v1, v29
	v_add_f32_e32 v2, v2, v30
	v_add_f32_e32 v3, v3, v31
	s_waitcnt vmcnt(0)
	v_fma_f32 v32, v0, 0.5, v32
	v_fma_f32 v33, v1, 0.5, v33
	v_fma_f32 v34, v2, 0.5, v34
	v_fma_f32 v35, v3, 0.5, v35
	global_store_dwordx4 v[168:169], v[32:35], off
	v_cvt_pk_bf16_f32 v36, v32, v33
	v_cvt_pk_bf16_f32 v37, v34, v35
	global_store_dwordx2 v[172:173], v[36:37], off
	v_mul_f32_e32 v38, v32, v32
	v_fmac_f32_e32 v38, v33, v33
	v_fmac_f32_e32 v38, v34, v34
	v_fmac_f32_e32 v38, v35, v35
	v_xor_b32_e32 v39, 16, v136
	v_lshlrev_b32_e32 v39, 2, v39
	ds_bpermute_b32 v40, v39, v38
	v_xor_b32_e32 v41, 32, v136
	v_lshlrev_b32_e32 v41, 2, v41
	s_waitcnt lgkmcnt(0)
	v_add_f32_e32 v38, v38, v40
	ds_bpermute_b32 v40, v41, v38
	s_waitcnt lgkmcnt(0)
	v_add_f32_e32 v38, v38, v40
	v_cmp_gt_u32_e64 s[82:83], 16, v136
	s_nop 1
	s_and_saveexec_b64 s[84:85], s[82:83]
	global_atomic_add_f32 v[166:167], v38, off
	s_mov_b64 exec, s[84:85]
.Lmg1_end:
	s_cmp_lt_u32 s33, 32
	s_cbranch_scc1 .Lcpy1_end
	v_lshrrev_b32_e32 v21, 6, v174
	v_and_b32_e32 v22, 63, v174
	v_lshlrev_b32_e32 v22, 4, v22
	v_readfirstlane_b32 s80, v21
	v_add_u32_e32 v23, 0x1000, v22
	v_readfirstlane_b32 s92, v235
	v_readfirstlane_b32 s93, v236
	v_readfirstlane_b32 s94, v237
	v_readfirstlane_b32 s95, v238
	v_readfirstlane_b32 s98, v239
	v_readfirstlane_b32 s99, v240
	s_add_i32 s80, s80, s33
	s_add_i32 s80, s80, 0x1f20
	s_sub_i32 s100, s78, 4
	s_lshl_b32 s100, s100, 3
.Lcpy1_loop:
	s_add_i32 s101, s80, s100
	s_cmp_lt_u32 s101, 0x4830
	s_cbranch_scc0 .Lcpy1_tail
	s_mul_hi_u32 s81, s80, 0x2ad5802b
	s_lshr_b32 s81, s81, 8
	s_mul_i32 s82, s81, 0x5fa
	s_sub_i32 s82, s80, s82
	s_lshl_b32 s82, s82, 13
	s_and_b32 s83, s81, 31
	s_mul_i32 s83, s83, 0xc00000
	s_add_i32 s82, s82, s83
	s_cmp_lt_u32 s81, 32
	s_cselect_b32 s84, s92, s94
	s_cselect_b32 s85, s93, s95
	s_mov_b32 s83, 0x1f210000
	s_cselect_b32 s83, 0x7210000, s83
	s_add_u32 s84, s84, s82
	s_addc_u32 s85, s85, 0
	s_add_u32 s84, s84, 0xc000
	s_addc_u32 s85, s85, 0
	s_add_u32 s83, s83, s82
	s_add_u32 s86, s98, s83
	s_addc_u32 s87, s99, 0
	s_mul_hi_u32 s81, s101, 0x2ad5802b
	s_lshr_b32 s81, s81, 8
	s_mul_i32 s82, s81, 0x5fa
	s_sub_i32 s82, s101, s82
	s_lshl_b32 s82, s82, 13
	s_and_b32 s83, s81, 31
	s_mul_i32 s83, s83, 0xc00000
	s_add_i32 s82, s82, s83
	s_cmp_lt_u32 s81, 32
	s_cselect_b32 s88, s92, s94
	s_cselect_b32 s89, s93, s95
	s_mov_b32 s83, 0x1f210000
	s_cselect_b32 s83, 0x7210000, s83
	s_add_u32 s88, s88, s82
	s_addc_u32 s89, s89, 0
	s_add_u32 s88, s88, 0xc000
	s_addc_u32 s89, s89, 0
	s_add_u32 s83, s83, s82
	s_add_u32 s90, s98, s83
	s_addc_u32 s91, s99, 0
	global_load_dwordx4 v[64:67], v22, s[84:85] nt
	global_load_dwordx4 v[68:71], v22, s[84:85] offset:1024 nt
	global_load_dwordx4 v[72:75], v22, s[84:85] offset:2048 nt
	global_load_dwordx4 v[76:79], v22, s[84:85] offset:3072 nt
	global_load_dwordx4 v[80:83], v23, s[84:85] nt
	global_load_dwordx4 v[84:87], v23, s[84:85] offset:1024 nt
	global_load_dwordx4 v[88:91], v23, s[84:85] offset:2048 nt
	global_load_dwordx4 v[92:95], v23, s[84:85] offset:3072 nt
	global_load_dwordx4 v[96:99], v22, s[88:89] nt
	global_load_dwordx4 v[100:103], v22, s[88:89] offset:1024 nt
	global_load_dwordx4 v[104:107], v22, s[88:89] offset:2048 nt
	global_load_dwordx4 v[108:111], v22, s[88:89] offset:3072 nt
	global_load_dwordx4 v[112:115], v23, s[88:89] nt
	global_load_dwordx4 v[116:119], v23, s[88:89] offset:1024 nt
	global_load_dwordx4 v[120:123], v23, s[88:89] offset:2048 nt
	global_load_dwordx4 v[124:127], v23, s[88:89] offset:3072 nt
	s_waitcnt vmcnt(15)
	global_store_dwordx4 v22, v[64:67], s[86:87] nt
	s_waitcnt vmcnt(15)
	global_store_dwordx4 v22, v[68:71], s[86:87] offset:1024 nt
	s_waitcnt vmcnt(15)
	global_store_dwordx4 v22, v[72:75], s[86:87] offset:2048 nt
	s_waitcnt vmcnt(15)
	global_store_dwordx4 v22, v[76:79], s[86:87] offset:3072 nt
	s_waitcnt vmcnt(15)
	global_store_dwordx4 v23, v[80:83], s[86:87] nt
	s_waitcnt vmcnt(15)
	global_store_dwordx4 v23, v[84:87], s[86:87] offset:1024 nt
	s_waitcnt vmcnt(15)
	global_store_dwordx4 v23, v[88:91], s[86:87] offset:2048 nt
	s_waitcnt vmcnt(15)
	global_store_dwordx4 v23, v[92:95], s[86:87] offset:3072 nt
	s_waitcnt vmcnt(15)
	global_store_dwordx4 v22, v[96:99], s[90:91] nt
	s_waitcnt vmcnt(15)
	global_store_dwordx4 v22, v[100:103], s[90:91] offset:1024 nt
	s_waitcnt vmcnt(15)
	global_store_dwordx4 v22, v[104:107], s[90:91] offset:2048 nt
	s_waitcnt vmcnt(15)
	global_store_dwordx4 v22, v[108:111], s[90:91] offset:3072 nt
	s_waitcnt vmcnt(15)
	global_store_dwordx4 v23, v[112:115], s[90:91] nt
	s_waitcnt vmcnt(15)
	global_store_dwordx4 v23, v[116:119], s[90:91] offset:1024 nt
	s_waitcnt vmcnt(15)
	global_store_dwordx4 v23, v[120:123], s[90:91] offset:2048 nt
	s_waitcnt vmcnt(15)
	global_store_dwordx4 v23, v[124:127], s[90:91] offset:3072 nt
	s_add_i32 s80, s101, s100
	s_branch .Lcpy1_loop
.Lcpy1_tail:
	s_cmp_lt_u32 s80, 0x4830
	s_cbranch_scc0 .Lcpy1_end
	s_mul_hi_u32 s81, s80, 0x2ad5802b
	s_lshr_b32 s81, s81, 8
	s_mul_i32 s82, s81, 0x5fa
	s_sub_i32 s82, s80, s82
	s_lshl_b32 s82, s82, 13
	s_and_b32 s83, s81, 31
	s_mul_i32 s83, s83, 0xc00000
	s_add_i32 s82, s82, s83
	s_cmp_lt_u32 s81, 32
	s_cselect_b32 s84, s92, s94
	s_cselect_b32 s85, s93, s95
	s_mov_b32 s83, 0x1f210000
	s_cselect_b32 s83, 0x7210000, s83
	s_add_u32 s84, s84, s82
	s_addc_u32 s85, s85, 0
	s_add_u32 s84, s84, 0xc000
	s_addc_u32 s85, s85, 0
	s_add_u32 s83, s83, s82
	s_add_u32 s86, s98, s83
	s_addc_u32 s87, s99, 0
	global_load_dwordx4 v[64:67], v22, s[84:85] nt
	global_load_dwordx4 v[68:71], v22, s[84:85] offset:1024 nt
	global_load_dwordx4 v[72:75], v22, s[84:85] offset:2048 nt
	global_load_dwordx4 v[76:79], v22, s[84:85] offset:3072 nt
	global_load_dwordx4 v[80:83], v23, s[84:85] nt
	global_load_dwordx4 v[84:87], v23, s[84:85] offset:1024 nt
	global_load_dwordx4 v[88:91], v23, s[84:85] offset:2048 nt
	global_load_dwordx4 v[92:95], v23, s[84:85] offset:3072 nt
	s_waitcnt vmcnt(7)
	global_store_dwordx4 v22, v[64:67], s[86:87] nt
	s_waitcnt vmcnt(7)
	global_store_dwordx4 v22, v[68:71], s[86:87] offset:1024 nt
	s_waitcnt vmcnt(7)
	global_store_dwordx4 v22, v[72:75], s[86:87] offset:2048 nt
	s_waitcnt vmcnt(7)
	global_store_dwordx4 v22, v[76:79], s[86:87] offset:3072 nt
	s_waitcnt vmcnt(7)
	global_store_dwordx4 v23, v[80:83], s[86:87] nt
	s_waitcnt vmcnt(7)
	global_store_dwordx4 v23, v[84:87], s[86:87] offset:1024 nt
	s_waitcnt vmcnt(7)
	global_store_dwordx4 v23, v[88:91], s[86:87] offset:2048 nt
	s_waitcnt vmcnt(7)
	global_store_dwordx4 v23, v[92:95], s[86:87] offset:3072 nt

.LBB0_412:
	s_cmp_lt_u32 s33, 64
	s_cbranch_scc1 .Lcpyb_end
	v_lshrrev_b32_e32 v21, 6, v174
	v_and_b32_e32 v22, 63, v174
	v_lshlrev_b32_e32 v22, 4, v22
	v_readfirstlane_b32 s80, v21
	v_add_u32_e32 v23, 0x1000, v22
	v_readfirstlane_b32 s92, v235
	v_readfirstlane_b32 s93, v236
	v_readfirstlane_b32 s94, v237
	v_readfirstlane_b32 s95, v238
	v_readfirstlane_b32 s98, v239
	v_readfirstlane_b32 s99, v240
	s_add_i32 s80, s80, s33
	s_add_i32 s80, s80, 0x47f0
	s_sub_i32 s100, s78, 8
	s_lshl_b32 s100, s100, 3
.Lcpyb_loop:
	s_add_i32 s101, s80, s100
	s_cmp_lt_u32 s101, 0x7710
	s_cbranch_scc0 .Lcpyb_tail
	s_mul_hi_u32 s81, s80, 0x2ad5802b
	s_lshr_b32 s81, s81, 8
	s_mul_i32 s82, s81, 0x5fa
	s_sub_i32 s82, s80, s82
	s_lshl_b32 s82, s82, 13
	s_and_b32 s83, s81, 31
	s_mul_i32 s83, s83, 0xc00000
	s_add_i32 s82, s82, s83
	s_cmp_lt_u32 s81, 32
	s_cselect_b32 s84, s92, s94
	s_cselect_b32 s85, s93, s95
	s_mov_b32 s83, 0x1f210000
	s_cselect_b32 s83, 0x7210000, s83
	s_add_u32 s84, s84, s82
	s_addc_u32 s85, s85, 0
	s_add_u32 s84, s84, 0xc000
	s_addc_u32 s85, s85, 0
	s_add_u32 s83, s83, s82
	s_add_u32 s86, s98, s83
	s_addc_u32 s87, s99, 0
	s_mul_hi_u32 s81, s101, 0x2ad5802b
	s_lshr_b32 s81, s81, 8
	s_mul_i32 s82, s81, 0x5fa
	s_sub_i32 s82, s101, s82
	s_lshl_b32 s82, s82, 13
	s_and_b32 s83, s81, 31
	s_mul_i32 s83, s83, 0xc00000
	s_add_i32 s82, s82, s83
	s_cmp_lt_u32 s81, 32
	s_cselect_b32 s88, s92, s94
	s_cselect_b32 s89, s93, s95
	s_mov_b32 s83, 0x1f210000
	s_cselect_b32 s83, 0x7210000, s83
	s_add_u32 s88, s88, s82
	s_addc_u32 s89, s89, 0
	s_add_u32 s88, s88, 0xc000
	s_addc_u32 s89, s89, 0
	s_add_u32 s83, s83, s82
	s_add_u32 s90, s98, s83
	s_addc_u32 s91, s99, 0
	global_load_dwordx4 v[64:67], v22, s[84:85] nt
	global_load_dwordx4 v[68:71], v22, s[84:85] offset:1024 nt
	global_load_dwordx4 v[72:75], v22, s[84:85] offset:2048 nt
	global_load_dwordx4 v[76:79], v22, s[84:85] offset:3072 nt
	global_load_dwordx4 v[80:83], v23, s[84:85] nt
	global_load_dwordx4 v[84:87], v23, s[84:85] offset:1024 nt
	global_load_dwordx4 v[88:91], v23, s[84:85] offset:2048 nt
	global_load_dwordx4 v[92:95], v23, s[84:85] offset:3072 nt
	global_load_dwordx4 v[96:99], v22, s[88:89] nt
	global_load_dwordx4 v[100:103], v22, s[88:89] offset:1024 nt
	global_load_dwordx4 v[104:107], v22, s[88:89] offset:2048 nt
	global_load_dwordx4 v[108:111], v22, s[88:89] offset:3072 nt
	global_load_dwordx4 v[112:115], v23, s[88:89] nt
	global_load_dwordx4 v[116:119], v23, s[88:89] offset:1024 nt
	global_load_dwordx4 v[120:123], v23, s[88:89] offset:2048 nt
	global_load_dwordx4 v[124:127], v23, s[88:89] offset:3072 nt
	s_waitcnt vmcnt(15)
	global_store_dwordx4 v22, v[64:67], s[86:87] nt
	s_waitcnt vmcnt(15)
	global_store_dwordx4 v22, v[68:71], s[86:87] offset:1024 nt
	s_waitcnt vmcnt(15)
	global_store_dwordx4 v22, v[72:75], s[86:87] offset:2048 nt
	s_waitcnt vmcnt(15)
	global_store_dwordx4 v22, v[76:79], s[86:87] offset:3072 nt
	s_waitcnt vmcnt(15)
	global_store_dwordx4 v23, v[80:83], s[86:87] nt
	s_waitcnt vmcnt(15)
	global_store_dwordx4 v23, v[84:87], s[86:87] offset:1024 nt
	s_waitcnt vmcnt(15)
	global_store_dwordx4 v23, v[88:91], s[86:87] offset:2048 nt
	s_waitcnt vmcnt(15)
	global_store_dwordx4 v23, v[92:95], s[86:87] offset:3072 nt
	s_waitcnt vmcnt(15)
	global_store_dwordx4 v22, v[96:99], s[90:91] nt
	s_waitcnt vmcnt(15)
	global_store_dwordx4 v22, v[100:103], s[90:91] offset:1024 nt
	s_waitcnt vmcnt(15)
	global_store_dwordx4 v22, v[104:107], s[90:91] offset:2048 nt
	s_waitcnt vmcnt(15)
	global_store_dwordx4 v22, v[108:111], s[90:91] offset:3072 nt
	s_waitcnt vmcnt(15)
	global_store_dwordx4 v23, v[112:115], s[90:91] nt
	s_waitcnt vmcnt(15)
	global_store_dwordx4 v23, v[116:119], s[90:91] offset:1024 nt
	s_waitcnt vmcnt(15)
	global_store_dwordx4 v23, v[120:123], s[90:91] offset:2048 nt
	s_waitcnt vmcnt(15)
	global_store_dwordx4 v23, v[124:127], s[90:91] offset:3072 nt
	s_add_i32 s80, s101, s100
	s_branch .Lcpyb_loop
.Lcpyb_tail:
	s_cmp_lt_u32 s80, 0x7710
	s_cbranch_scc0 .Lcpyb_end
	s_mul_hi_u32 s81, s80, 0x2ad5802b
	s_lshr_b32 s81, s81, 8
	s_mul_i32 s82, s81, 0x5fa
	s_sub_i32 s82, s80, s82
	s_lshl_b32 s82, s82, 13
	s_and_b32 s83, s81, 31
	s_mul_i32 s83, s83, 0xc00000
	s_add_i32 s82, s82, s83
	s_cmp_lt_u32 s81, 32
	s_cselect_b32 s84, s92, s94
	s_cselect_b32 s85, s93, s95
	s_mov_b32 s83, 0x1f210000
	s_cselect_b32 s83, 0x7210000, s83
	s_add_u32 s84, s84, s82
	s_addc_u32 s85, s85, 0
	s_add_u32 s84, s84, 0xc000
	s_addc_u32 s85, s85, 0
	s_add_u32 s83, s83, s82
	s_add_u32 s86, s98, s83
	s_addc_u32 s87, s99, 0
	global_load_dwordx4 v[64:67], v22, s[84:85] nt
	global_load_dwordx4 v[68:71], v22, s[84:85] offset:1024 nt
	global_load_dwordx4 v[72:75], v22, s[84:85] offset:2048 nt
	global_load_dwordx4 v[76:79], v22, s[84:85] offset:3072 nt
	global_load_dwordx4 v[80:83], v23, s[84:85] nt
	global_load_dwordx4 v[84:87], v23, s[84:85] offset:1024 nt
	global_load_dwordx4 v[88:91], v23, s[84:85] offset:2048 nt
	global_load_dwordx4 v[92:95], v23, s[84:85] offset:3072 nt
	s_waitcnt vmcnt(7)
	global_store_dwordx4 v22, v[64:67], s[86:87] nt
	s_waitcnt vmcnt(7)
	global_store_dwordx4 v22, v[68:71], s[86:87] offset:1024 nt
	s_waitcnt vmcnt(7)
	global_store_dwordx4 v22, v[72:75], s[86:87] offset:2048 nt
	s_waitcnt vmcnt(7)
	global_store_dwordx4 v22, v[76:79], s[86:87] offset:3072 nt
	s_waitcnt vmcnt(7)
	global_store_dwordx4 v23, v[80:83], s[86:87] nt
	s_waitcnt vmcnt(7)
	global_store_dwordx4 v23, v[84:87], s[86:87] offset:1024 nt
	s_waitcnt vmcnt(7)
	global_store_dwordx4 v23, v[88:91], s[86:87] offset:2048 nt
	s_waitcnt vmcnt(7)
	global_store_dwordx4 v23, v[92:95], s[86:87] offset:3072 nt

.LBB0_452:
	s_cmp_lt_u32 s33, 1200
	s_cbranch_scc1 .Lcpyc_end
	v_lshrrev_b32_e32 v21, 6, v174
	v_and_b32_e32 v22, 63, v174
	v_lshlrev_b32_e32 v22, 4, v22
	v_readfirstlane_b32 s80, v21
	v_add_u32_e32 v23, 0x1000, v22
	v_readfirstlane_b32 s92, v235
	v_readfirstlane_b32 s93, v236
	v_readfirstlane_b32 s94, v237
	v_readfirstlane_b32 s95, v238
	v_readfirstlane_b32 s98, v239
	v_readfirstlane_b32 s99, v240
	s_add_i32 s80, s80, s33
	s_add_i32 s80, s80, 0x7260
	s_sub_i32 s100, s78, 150
	s_lshl_b32 s100, s100, 3
.Lcpyc_loop:
	s_add_i32 s101, s80, s100
	s_cmp_lt_u32 s101, 0x9650
	s_cbranch_scc0 .Lcpyc_tail
	s_mul_hi_u32 s81, s80, 0x2ad5802b
	s_lshr_b32 s81, s81, 8
	s_mul_i32 s82, s81, 0x5fa
	s_sub_i32 s82, s80, s82
	s_lshl_b32 s82, s82, 13
	s_and_b32 s83, s81, 31
	s_mul_i32 s83, s83, 0xc00000
	s_add_i32 s82, s82, s83
	s_cmp_lt_u32 s81, 32
	s_cselect_b32 s84, s92, s94
	s_cselect_b32 s85, s93, s95
	s_mov_b32 s83, 0x1f210000
	s_cselect_b32 s83, 0x7210000, s83
	s_add_u32 s84, s84, s82
	s_addc_u32 s85, s85, 0
	s_add_u32 s84, s84, 0xc000
	s_addc_u32 s85, s85, 0
	s_add_u32 s83, s83, s82
	s_add_u32 s86, s98, s83
	s_addc_u32 s87, s99, 0
	s_mul_hi_u32 s81, s101, 0x2ad5802b
	s_lshr_b32 s81, s81, 8
	s_mul_i32 s82, s81, 0x5fa
	s_sub_i32 s82, s101, s82
	s_lshl_b32 s82, s82, 13
	s_and_b32 s83, s81, 31
	s_mul_i32 s83, s83, 0xc00000
	s_add_i32 s82, s82, s83
	s_cmp_lt_u32 s81, 32
	s_cselect_b32 s88, s92, s94
	s_cselect_b32 s89, s93, s95
	s_mov_b32 s83, 0x1f210000
	s_cselect_b32 s83, 0x7210000, s83
	s_add_u32 s88, s88, s82
	s_addc_u32 s89, s89, 0
	s_add_u32 s88, s88, 0xc000
	s_addc_u32 s89, s89, 0
	s_add_u32 s83, s83, s82
	s_add_u32 s90, s98, s83
	s_addc_u32 s91, s99, 0
	global_load_dwordx4 v[64:67], v22, s[84:85] nt
	global_load_dwordx4 v[68:71], v22, s[84:85] offset:1024 nt
	global_load_dwordx4 v[72:75], v22, s[84:85] offset:2048 nt
	global_load_dwordx4 v[76:79], v22, s[84:85] offset:3072 nt
	global_load_dwordx4 v[80:83], v23, s[84:85] nt
	global_load_dwordx4 v[84:87], v23, s[84:85] offset:1024 nt
	global_load_dwordx4 v[88:91], v23, s[84:85] offset:2048 nt
	global_load_dwordx4 v[92:95], v23, s[84:85] offset:3072 nt
	global_load_dwordx4 v[96:99], v22, s[88:89] nt
	global_load_dwordx4 v[100:103], v22, s[88:89] offset:1024 nt
	global_load_dwordx4 v[104:107], v22, s[88:89] offset:2048 nt
	global_load_dwordx4 v[108:111], v22, s[88:89] offset:3072 nt
	global_load_dwordx4 v[112:115], v23, s[88:89] nt
	global_load_dwordx4 v[116:119], v23, s[88:89] offset:1024 nt
	global_load_dwordx4 v[120:123], v23, s[88:89] offset:2048 nt
	global_load_dwordx4 v[124:127], v23, s[88:89] offset:3072 nt
	s_waitcnt vmcnt(15)
	global_store_dwordx4 v22, v[64:67], s[86:87] nt
	s_waitcnt vmcnt(15)
	global_store_dwordx4 v22, v[68:71], s[86:87] offset:1024 nt
	s_waitcnt vmcnt(15)
	global_store_dwordx4 v22, v[72:75], s[86:87] offset:2048 nt
	s_waitcnt vmcnt(15)
	global_store_dwordx4 v22, v[76:79], s[86:87] offset:3072 nt
	s_waitcnt vmcnt(15)
	global_store_dwordx4 v23, v[80:83], s[86:87] nt
	s_waitcnt vmcnt(15)
	global_store_dwordx4 v23, v[84:87], s[86:87] offset:1024 nt
	s_waitcnt vmcnt(15)
	global_store_dwordx4 v23, v[88:91], s[86:87] offset:2048 nt
	s_waitcnt vmcnt(15)
	global_store_dwordx4 v23, v[92:95], s[86:87] offset:3072 nt
	s_waitcnt vmcnt(15)
	global_store_dwordx4 v22, v[96:99], s[90:91] nt
	s_waitcnt vmcnt(15)
	global_store_dwordx4 v22, v[100:103], s[90:91] offset:1024 nt
	s_waitcnt vmcnt(15)
	global_store_dwordx4 v22, v[104:107], s[90:91] offset:2048 nt
	s_waitcnt vmcnt(15)
	global_store_dwordx4 v22, v[108:111], s[90:91] offset:3072 nt
	s_waitcnt vmcnt(15)
	global_store_dwordx4 v23, v[112:115], s[90:91] nt
	s_waitcnt vmcnt(15)
	global_store_dwordx4 v23, v[116:119], s[90:91] offset:1024 nt
	s_waitcnt vmcnt(15)
	global_store_dwordx4 v23, v[120:123], s[90:91] offset:2048 nt
	s_waitcnt vmcnt(15)
	global_store_dwordx4 v23, v[124:127], s[90:91] offset:3072 nt
	s_add_i32 s80, s101, s100
	s_branch .Lcpyc_loop
.Lcpyc_tail:
	s_cmp_lt_u32 s80, 0x9650
	s_cbranch_scc0 .Lcpyc_end
	s_mul_hi_u32 s81, s80, 0x2ad5802b
	s_lshr_b32 s81, s81, 8
	s_mul_i32 s82, s81, 0x5fa
	s_sub_i32 s82, s80, s82
	s_lshl_b32 s82, s82, 13
	s_and_b32 s83, s81, 31
	s_mul_i32 s83, s83, 0xc00000
	s_add_i32 s82, s82, s83
	s_cmp_lt_u32 s81, 32
	s_cselect_b32 s84, s92, s94
	s_cselect_b32 s85, s93, s95
	s_mov_b32 s83, 0x1f210000
	s_cselect_b32 s83, 0x7210000, s83
	s_add_u32 s84, s84, s82
	s_addc_u32 s85, s85, 0
	s_add_u32 s84, s84, 0xc000
	s_addc_u32 s85, s85, 0
	s_add_u32 s83, s83, s82
	s_add_u32 s86, s98, s83
	s_addc_u32 s87, s99, 0
	global_load_dwordx4 v[64:67], v22, s[84:85] nt
	global_load_dwordx4 v[68:71], v22, s[84:85] offset:1024 nt
	global_load_dwordx4 v[72:75], v22, s[84:85] offset:2048 nt
	global_load_dwordx4 v[76:79], v22, s[84:85] offset:3072 nt
	global_load_dwordx4 v[80:83], v23, s[84:85] nt
	global_load_dwordx4 v[84:87], v23, s[84:85] offset:1024 nt
	global_load_dwordx4 v[88:91], v23, s[84:85] offset:2048 nt
	global_load_dwordx4 v[92:95], v23, s[84:85] offset:3072 nt
	s_waitcnt vmcnt(7)
	global_store_dwordx4 v22, v[64:67], s[86:87] nt
	s_waitcnt vmcnt(7)
	global_store_dwordx4 v22, v[68:71], s[86:87] offset:1024 nt
	s_waitcnt vmcnt(7)
	global_store_dwordx4 v22, v[72:75], s[86:87] offset:2048 nt
	s_waitcnt vmcnt(7)
	global_store_dwordx4 v22, v[76:79], s[86:87] offset:3072 nt
	s_waitcnt vmcnt(7)
	global_store_dwordx4 v23, v[80:83], s[86:87] nt
	s_waitcnt vmcnt(7)
	global_store_dwordx4 v23, v[84:87], s[86:87] offset:1024 nt
	s_waitcnt vmcnt(7)
	global_store_dwordx4 v23, v[88:91], s[86:87] offset:2048 nt
	s_waitcnt vmcnt(7)
	global_store_dwordx4 v23, v[92:95], s[86:87] offset:3072 nt

.LBB0_472:
	s_or_b64 exec, exec, s[8:9]
	v_readlane_b32 s4, v234, 2
	v_mov_b32_e32 v8, v174
	v_readlane_b32 s5, v234, 3
	s_barrier
	s_and_b64 vcc, exec, s[4:5]
	v_readfirstlane_b32 s4, v8
	s_cbranch_vccnz .LBB0_478
	s_ashr_i32 s5, s2, 31
	s_lshr_b32 s5, s5, 29
	s_add_i32 s5, s2, s5
	s_and_b32 s6, s5, -8
	s_sub_i32 s6, s2, s6
	s_cmp_gt_i32 s6, -1
	s_cbranch_scc0 .LBB0_475
	s_lshl_b32 s7, s6, 5
	s_or_b32 s7, s7, 0
	s_cbranch_execz .LBB0_476
	s_branch .LBB0_477

.LBB0_481:
	s_lshl_b32 s9, s9, 5
	s_mov_b64 s[16:17], 0x80
	s_and_b32 s14, s9, 0x60
	s_add_i32 m0, s30, 0x18000
	v_lshl_add_u64 v[6:7], v[6:7], 0, s[16:17]
	s_lshl_b32 s11, s8, 13
	s_lshl_b32 s9, s14, 7
	s_waitcnt vmcnt(4)
	s_barrier
	global_load_lds_dwordx4 v[6:7], off
	v_lshl_add_u64 v[4:5], v[4:5], 0, s[16:17]
	s_add_i32 m0, s30, 0x1a000
	s_add_i32 s37, s30, 0x8000
	s_add_i32 s42, s30, 0xa000
	global_load_lds_dwordx4 v[4:5], off
	v_lshl_add_u64 v[2:3], v[2:3], 0, s[16:17]
	s_mov_b32 m0, s37
	s_add_u32 s12, s22, 0xb0080
	global_load_lds_dwordx4 v[2:3], off
	v_lshl_add_u64 v[0:1], v[0:1], 0, s[16:17]
	s_mov_b32 m0, s42
	s_addc_u32 s13, s23, 0
	global_load_lds_dwordx4 v[0:1], off
	s_add_i32 m0, s30, 0x1c000
	v_lshl_add_u64 v[0:1], s[12:13], 0, v[130:131]
	global_load_lds_dwordx4 v[0:1], off
	v_lshl_add_u64 v[0:1], s[12:13], 0, v[134:135]
	s_add_i32 m0, s30, 0x1e000
	s_mov_b64 s[12:13], 0xb0080
	global_load_lds_dwordx4 v[0:1], off
	v_bfe_u32 v0, v8, 4, 2
	v_and_b32_e32 v1, 15, v8
	v_lshlrev_b32_e32 v2, 4, v0
	v_lshl_or_b32 v148, s8, 6, v1
	v_lshl_or_b32 v1, v1, 6, v2
	v_lshlrev_b32_e32 v2, 2, v8
	v_and_b32_e32 v2, 32, v2
	v_bitop3_b32 v3, v1, s11, v2 bitop3:0xde
	v_bitop3_b32 v149, v1, s9, v2 bitop3:0xde
	v_cmp_eq_u32_e64 s[8:9], 0, v0
	v_lshl_or_b32 v150, v0, 3, s14
	v_lshrrev_b32_e32 v1, 1, v9
	v_mul_lo_u32 v0, v11, s10
	s_mov_b32 s11, 0xb000
	v_mad_u64_u32 v[0:1], s[14:15], v1, s11, v[0:1]
	v_or_b32_e32 v0, v0, v10
	v_add_lshl_u32 v0, v0, v12, 1
	v_mov_b32_e32 v1, v131
	v_lshl_add_u64 v[136:137], v[0:1], 0, s[12:13]
	v_lshrrev_b32_e32 v1, 1, v13
	v_mul_lo_u32 v0, v14, s10
	v_mad_u64_u32 v[0:1], s[10:11], v1, s11, v[0:1]
	s_waitcnt vmcnt(6)
	v_or_b32_e32 v0, v0, v15
	v_add_lshl_u32 v0, v0, v16, 1
	v_mov_b32_e32 v1, v131
	s_add_i32 s47, 0, 0x10000
	s_add_i32 s52, 0, 0x14000
	s_bfe_i64 s[18:19], s[78:79], 0x200000
	s_ashr_i32 s43, s2, 31
	s_mov_b32 s46, s2
	v_lshl_add_u64 v[138:139], v[0:1], 0, s[12:13]
	v_mov_b64_e32 v[140:141], 0x100
	v_mov_b64_e32 v[142:143], 0xff
	v_add_u32_e32 v151, s47, v149
	v_add_u32_e32 v152, 0, v3
	v_add_u32_e32 v153, s52, v149
	v_mbcnt_hi_u32_b32 v154, -1, v175
	s_barrier
	s_branch .LBB0_483

.LBB0_514:
	v_and_b32_e32 v160, 15, v174
	v_bfe_u32 v161, v174, 4, 2
	v_lshrrev_b32_e32 v162, 6, v174
	v_and_b32_e32 v136, 63, v174
	v_readfirstlane_b32 s80, v162
	s_lshr_b32 s81, s33, 8
	s_lshr_b32 s82, s33, 3
	s_and_b32 s82, s82, 31
	s_mul_i32 s83, s80, 704
	v_lshlrev_b32_e32 v164, 4, v161
	v_mov_b32_e32 v167, 0
	s_lshl_b32 s84, s82, 5
	v_add_u32_e32 v165, s84, v160
	v_mul_u32_u24_e32 v166, 0x1600, v165
	v_add3_u32 v166, v166, v164, s83
	s_add_u32 s86, s74, 0x3700000
	s_addc_u32 s87, s75, 0
	s_mov_b32 s88, 0x16000
	s_mov_b32 s89, 0
	v_lshl_add_u64 v[152:153], s[86:87], 0, v[166:167]
	v_lshl_add_u64 v[154:155], v[152:153], 0, s[88:89]
	s_lshl_b32 s84, s81, 5
	v_add_u32_e32 v165, s84, v160
	v_mul_u32_u24_e32 v166, 0x1600, v165
	v_add3_u32 v166, v166, v164, s83
	s_add_u32 s90, s74, 0x10980000
	s_addc_u32 s91, s75, 0
	v_lshl_add_u64 v[156:157], s[90:91], 0, v[166:167]
	v_lshl_add_u64 v[158:159], v[156:157], 0, s[88:89]
	v_mov_b32_e32 v128, 0
	v_mov_b32_e32 v129, 0
	v_mov_b32_e32 v130, 0
	v_mov_b32_e32 v131, 0
	v_mov_b32_e32 v132, 0
	v_mov_b32_e32 v133, 0
	v_mov_b32_e32 v134, 0
	v_mov_b32_e32 v135, 0
	v_mov_b32_e32 v144, 0
	v_mov_b32_e32 v145, 0
	v_mov_b32_e32 v146, 0
	v_mov_b32_e32 v147, 0
	v_mov_b32_e32 v148, 0
	v_mov_b32_e32 v149, 0
	v_mov_b32_e32 v150, 0
	v_mov_b32_e32 v151, 0
	global_load_dwordx4 v[0:3], v[152:153], off
	global_load_dwordx4 v[4:7], v[154:155], off
	global_load_dwordx4 v[8:11], v[156:157], off
	global_load_dwordx4 v[12:15], v[158:159], off
	global_load_dwordx4 v[16:19], v[152:153], off offset:64
	global_load_dwordx4 v[20:23], v[154:155], off offset:64
	global_load_dwordx4 v[24:27], v[156:157], off offset:64
	global_load_dwordx4 v[28:31], v[158:159], off offset:64
	global_load_dwordx4 v[32:35], v[152:153], off offset:128
	global_load_dwordx4 v[36:39], v[154:155], off offset:128
	global_load_dwordx4 v[40:43], v[156:157], off offset:128
	global_load_dwordx4 v[44:47], v[158:159], off offset:128
	global_load_dwordx4 v[48:51], v[152:153], off offset:192
	global_load_dwordx4 v[52:55], v[154:155], off offset:192
	global_load_dwordx4 v[56:59], v[156:157], off offset:192
	global_load_dwordx4 v[60:63], v[158:159], off offset:192
	global_load_dwordx4 v[64:67], v[152:153], off offset:256
	global_load_dwordx4 v[68:71], v[154:155], off offset:256
	global_load_dwordx4 v[72:75], v[156:157], off offset:256
	global_load_dwordx4 v[76:79], v[158:159], off offset:256
	global_load_dwordx4 v[80:83], v[152:153], off offset:320
	global_load_dwordx4 v[84:87], v[154:155], off offset:320
	global_load_dwordx4 v[88:91], v[156:157], off offset:320
	global_load_dwordx4 v[92:95], v[158:159], off offset:320
	global_load_dwordx4 v[96:99], v[152:153], off offset:384
	global_load_dwordx4 v[100:103], v[154:155], off offset:384
	global_load_dwordx4 v[104:107], v[156:157], off offset:384
	global_load_dwordx4 v[108:111], v[158:159], off offset:384
	global_load_dwordx4 v[112:115], v[152:153], off offset:448
	global_load_dwordx4 v[116:119], v[154:155], off offset:448
	global_load_dwordx4 v[120:123], v[156:157], off offset:448
	global_load_dwordx4 v[124:127], v[158:159], off offset:448
	s_waitcnt vmcnt(16)
	v_mfma_f32_16x16x32_bf16 v[128:131], v[0:3], v[8:11], v[128:131]
	v_mfma_f32_16x16x32_bf16 v[132:135], v[4:7], v[8:11], v[132:135]
	v_mfma_f32_16x16x32_bf16 v[144:147], v[0:3], v[12:15], v[144:147]
	v_mfma_f32_16x16x32_bf16 v[148:151], v[4:7], v[12:15], v[148:151]
	v_mfma_f32_16x16x32_bf16 v[128:131], v[16:19], v[24:27], v[128:131]
	v_mfma_f32_16x16x32_bf16 v[132:135], v[20:23], v[24:27], v[132:135]
	v_mfma_f32_16x16x32_bf16 v[144:147], v[16:19], v[28:31], v[144:147]
	v_mfma_f32_16x16x32_bf16 v[148:151], v[20:23], v[28:31], v[148:151]
	v_mfma_f32_16x16x32_bf16 v[128:131], v[32:35], v[40:43], v[128:131]
	v_mfma_f32_16x16x32_bf16 v[132:135], v[36:39], v[40:43], v[132:135]
	v_mfma_f32_16x16x32_bf16 v[144:147], v[32:35], v[44:47], v[144:147]
	v_mfma_f32_16x16x32_bf16 v[148:151], v[36:39], v[44:47], v[148:151]
	v_mfma_f32_16x16x32_bf16 v[128:131], v[48:51], v[56:59], v[128:131]
	v_mfma_f32_16x16x32_bf16 v[132:135], v[52:55], v[56:59], v[132:135]
	v_mfma_f32_16x16x32_bf16 v[144:147], v[48:51], v[60:63], v[144:147]
	v_mfma_f32_16x16x32_bf16 v[148:151], v[52:55], v[60:63], v[148:151]
	global_load_dwordx4 v[0:3], v[152:153], off offset:512
	global_load_dwordx4 v[4:7], v[154:155], off offset:512
	global_load_dwordx4 v[8:11], v[156:157], off offset:512
	global_load_dwordx4 v[12:15], v[158:159], off offset:512
	global_load_dwordx4 v[16:19], v[152:153], off offset:576
	global_load_dwordx4 v[20:23], v[154:155], off offset:576
	global_load_dwordx4 v[24:27], v[156:157], off offset:576
	global_load_dwordx4 v[28:31], v[158:159], off offset:576
	global_load_dwordx4 v[32:35], v[152:153], off offset:640
	global_load_dwordx4 v[36:39], v[154:155], off offset:640
	global_load_dwordx4 v[40:43], v[156:157], off offset:640
	global_load_dwordx4 v[44:47], v[158:159], off offset:640
	s_waitcnt vmcnt(12)
	v_mfma_f32_16x16x32_bf16 v[128:131], v[64:67], v[72:75], v[128:131]
	v_mfma_f32_16x16x32_bf16 v[132:135], v[68:71], v[72:75], v[132:135]
	v_mfma_f32_16x16x32_bf16 v[144:147], v[64:67], v[76:79], v[144:147]
	v_mfma_f32_16x16x32_bf16 v[148:151], v[68:71], v[76:79], v[148:151]
	v_mfma_f32_16x16x32_bf16 v[128:131], v[80:83], v[88:91], v[128:131]
	v_mfma_f32_16x16x32_bf16 v[132:135], v[84:87], v[88:91], v[132:135]
	v_mfma_f32_16x16x32_bf16 v[144:147], v[80:83], v[92:95], v[144:147]
	v_mfma_f32_16x16x32_bf16 v[148:151], v[84:87], v[92:95], v[148:151]
	v_mfma_f32_16x16x32_bf16 v[128:131], v[96:99], v[104:107], v[128:131]
	v_mfma_f32_16x16x32_bf16 v[132:135], v[100:103], v[104:107], v[132:135]
	v_mfma_f32_16x16x32_bf16 v[144:147], v[96:99], v[108:111], v[144:147]
	v_mfma_f32_16x16x32_bf16 v[148:151], v[100:103], v[108:111], v[148:151]
	v_mfma_f32_16x16x32_bf16 v[128:131], v[112:115], v[120:123], v[128:131]
	v_mfma_f32_16x16x32_bf16 v[132:135], v[116:119], v[120:123], v[132:135]
	v_mfma_f32_16x16x32_bf16 v[144:147], v[112:115], v[124:127], v[144:147]
	v_mfma_f32_16x16x32_bf16 v[148:151], v[116:119], v[124:127], v[148:151]
	s_waitcnt vmcnt(0)
	v_mfma_f32_16x16x32_bf16 v[128:131], v[0:3], v[8:11], v[128:131]
	v_mfma_f32_16x16x32_bf16 v[132:135], v[4:7], v[8:11], v[132:135]
	v_mfma_f32_16x16x32_bf16 v[144:147], v[0:3], v[12:15], v[144:147]
	v_mfma_f32_16x16x32_bf16 v[148:151], v[4:7], v[12:15], v[148:151]
	v_mfma_f32_16x16x32_bf16 v[128:131], v[16:19], v[24:27], v[128:131]
	v_mfma_f32_16x16x32_bf16 v[132:135], v[20:23], v[24:27], v[132:135]
	v_mfma_f32_16x16x32_bf16 v[144:147], v[16:19], v[28:31], v[144:147]
	v_mfma_f32_16x16x32_bf16 v[148:151], v[20:23], v[28:31], v[148:151]
	v_mfma_f32_16x16x32_bf16 v[128:131], v[32:35], v[40:43], v[128:131]
	v_mfma_f32_16x16x32_bf16 v[132:135], v[36:39], v[40:43], v[132:135]
	v_mfma_f32_16x16x32_bf16 v[144:147], v[32:35], v[44:47], v[144:147]
	v_mfma_f32_16x16x32_bf16 v[148:151], v[36:39], v[44:47], v[148:151]
	s_nop 7
	s_nop 7
	v_lshlrev_b32_e32 v170, 12, v162
	v_lshl_add_u32 v170, v136, 4, v170
	ds_write_b128 v170, v[128:131]
	ds_write_b128 v170, v[132:135] offset:1024
	ds_write_b128 v170, v[144:147] offset:2048
	ds_write_b128 v170, v[148:151] offset:3072
	s_waitcnt lgkmcnt(0)
	s_barrier
	s_cmp_ge_u32 s80, 4
	s_cbranch_scc1 .Lmg2_end
	s_lshl_b32 s84, s80, 10
	v_lshlrev_b32_e32 v171, 4, v136
	v_add_u32_e32 v171, s84, v171
	ds_read_b128 v[0:3], v171
	ds_read_b128 v[4:7], v171 offset:4096
	ds_read_b128 v[8:11], v171 offset:8192
	ds_read_b128 v[12:15], v171 offset:12288
	ds_read_b128 v[16:19], v171 offset:16384
	ds_read_b128 v[20:23], v171 offset:20480
	ds_read_b128 v[24:27], v171 offset:24576
	ds_read_b128 v[28:31], v171 offset:28672
	s_lshr_b32 s84, s80, 1
	s_lshl_b32 s84, s84, 4
	s_lshl_b32 s85, s81, 5
	s_add_i32 s84, s84, s85
	s_addk_i32 s84, 0x4000
	s_and_b32 s85, s80, 1
	s_lshl_b32 s85, s85, 4
	s_lshl_b32 s83, s82, 5
	s_add_i32 s85, s85, s83
	v_add_u32_e32 v165, s84, v160
	v_lshl_add_u32 v164, v161, 2, s85
	v_lshlrev_b32_e32 v166, 12, v165
	v_lshl_add_u32 v166, v164, 2, v166
	v_mov_b32_e32 v167, 0
	s_add_u32 s86, s74, 0x5000000
	s_addc_u32 s87, s75, 0
	v_lshl_add_u64 v[168:169], s[86:87], 0, v[166:167]
	global_load_dwordx4 v[32:35], v[168:169], off
	v_lshrrev_b32_e32 v172, 1, v166
	v_mov_b32_e32 v173, 0
	s_add_u32 s86, s74, 0x9100000
	s_addc_u32 s87, s75, 0
	v_lshl_add_u64 v[172:173], s[86:87], 0, v[172:173]
	v_lshlrev_b32_e32 v166, 2, v165
	s_add_u32 s86, s74, 0x12b90c00
	s_addc_u32 s87, s75, 0
	v_lshl_add_u64 v[166:167], s[86:87], 0, v[166:167]
	s_waitcnt lgkmcnt(0)
	v_add_f32_e32 v0, v0, v4
	v_add_f32_e32 v1, v1, v5
	v_add_f32_e32 v2, v2, v6
	v_add_f32_e32 v3, v3, v7
	v_add_f32_e32 v0, v0, v8
	v_add_f32_e32 v1, v1, v9
	v_add_f32_e32 v2, v2, v10
	v_add_f32_e32 v3, v3, v11
	v_add_f32_e32 v0, v0, v12
	v_add_f32_e32 v1, v1, v13
	v_add_f32_e32 v2, v2, v14
	v_add_f32_e32 v3, v3, v15
	v_add_f32_e32 v0, v0, v16
	v_add_f32_e32 v1, v1, v17
	v_add_f32_e32 v2, v2, v18
	v_add_f32_e32 v3, v3, v19
	v_add_f32_e32 v0, v0, v20
	v_add_f32_e32 v1, v1, v21
	v_add_f32_e32 v2, v2, v22
	v_add_f32_e32 v3, v3, v23
	v_add_f32_e32 v0, v0, v24
	v_add_f32_e32 v1, v1, v25
	v_add_f32_e32 v2, v2, v26
	v_add_f32_e32 v3, v3, v27
	v_add_f32_e32 v0, v0, v28
	v_add_f32_e32 v1, v1, v29
	v_add_f32_e32 v2, v2, v30
	v_add_f32_e32 v3, v3, v31
	s_waitcnt vmcnt(0)
	v_fma_f32 v32, v0, 0.5, v32
	v_fma_f32 v33, v1, 0.5, v33
	v_fma_f32 v34, v2, 0.5, v34
	v_fma_f32 v35, v3, 0.5, v35
	global_store_dwordx4 v[168:169], v[32:35], off
	v_cvt_pk_bf16_f32 v36, v32, v33
	v_cvt_pk_bf16_f32 v37, v34, v35
	global_store_dwordx2 v[172:173], v[36:37], off
	v_mul_f32_e32 v38, v32, v32
	v_fmac_f32_e32 v38, v33, v33
	v_fmac_f32_e32 v38, v34, v34
	v_fmac_f32_e32 v38, v35, v35
	v_xor_b32_e32 v39, 16, v136
	v_lshlrev_b32_e32 v39, 2, v39
	ds_bpermute_b32 v40, v39, v38
	v_xor_b32_e32 v41, 32, v136
	v_lshlrev_b32_e32 v41, 2, v41
	s_waitcnt lgkmcnt(0)
	v_add_f32_e32 v38, v38, v40
	ds_bpermute_b32 v40, v41, v38
	s_waitcnt lgkmcnt(0)
	v_add_f32_e32 v38, v38, v40
	v_cmp_gt_u32_e64 s[82:83], 16, v136
	s_nop 1
	s_and_saveexec_b64 s[84:85], s[82:83]
	global_atomic_add_f32 v[166:167], v38, off
	s_mov_b64 exec, s[84:85]
.Lmg2_end:
	s_cmp_lt_u32 s33, 32
	s_cbranch_scc1 .Lcpy2_end
	v_lshrrev_b32_e32 v21, 6, v174
	v_and_b32_e32 v22, 63, v174
	v_lshlrev_b32_e32 v22, 4, v22
	v_readfirstlane_b32 s80, v21
	v_add_u32_e32 v23, 0x1000, v22
	v_readfirstlane_b32 s92, v235
	v_readfirstlane_b32 s93, v236
	v_readfirstlane_b32 s94, v237
	v_readfirstlane_b32 s95, v238
	v_readfirstlane_b32 s98, v239
	v_readfirstlane_b32 s99, v240
	s_add_i32 s80, s80, s33
	s_add_i32 s80, s80, 0x9630
	s_sub_i32 s100, s78, 4
	s_lshl_b32 s100, s100, 3
.Lcpy2_loop:
	s_add_i32 s101, s80, s100
	s_cmp_lt_u32 s101, 0xbf40
	s_cbranch_scc0 .Lcpy2_tail
	s_mul_hi_u32 s81, s80, 0x2ad5802b
	s_lshr_b32 s81, s81, 8
	s_mul_i32 s82, s81, 0x5fa
	s_sub_i32 s82, s80, s82
	s_lshl_b32 s82, s82, 13
	s_and_b32 s83, s81, 31
	s_mul_i32 s83, s83, 0xc00000
	s_add_i32 s82, s82, s83
	s_cmp_lt_u32 s81, 32
	s_cselect_b32 s84, s92, s94
	s_cselect_b32 s85, s93, s95
	s_mov_b32 s83, 0x1f210000
	s_cselect_b32 s83, 0x7210000, s83
	s_add_u32 s84, s84, s82
	s_addc_u32 s85, s85, 0
	s_add_u32 s84, s84, 0xc000
	s_addc_u32 s85, s85, 0
	s_add_u32 s83, s83, s82
	s_add_u32 s86, s98, s83
	s_addc_u32 s87, s99, 0
	s_mul_hi_u32 s81, s101, 0x2ad5802b
	s_lshr_b32 s81, s81, 8
	s_mul_i32 s82, s81, 0x5fa
	s_sub_i32 s82, s101, s82
	s_lshl_b32 s82, s82, 13
	s_and_b32 s83, s81, 31
	s_mul_i32 s83, s83, 0xc00000
	s_add_i32 s82, s82, s83
	s_cmp_lt_u32 s81, 32
	s_cselect_b32 s88, s92, s94
	s_cselect_b32 s89, s93, s95
	s_mov_b32 s83, 0x1f210000
	s_cselect_b32 s83, 0x7210000, s83
	s_add_u32 s88, s88, s82
	s_addc_u32 s89, s89, 0
	s_add_u32 s88, s88, 0xc000
	s_addc_u32 s89, s89, 0
	s_add_u32 s83, s83, s82
	s_add_u32 s90, s98, s83
	s_addc_u32 s91, s99, 0
	global_load_dwordx4 v[64:67], v22, s[84:85] nt
	global_load_dwordx4 v[68:71], v22, s[84:85] offset:1024 nt
	global_load_dwordx4 v[72:75], v22, s[84:85] offset:2048 nt
	global_load_dwordx4 v[76:79], v22, s[84:85] offset:3072 nt
	global_load_dwordx4 v[80:83], v23, s[84:85] nt
	global_load_dwordx4 v[84:87], v23, s[84:85] offset:1024 nt
	global_load_dwordx4 v[88:91], v23, s[84:85] offset:2048 nt
	global_load_dwordx4 v[92:95], v23, s[84:85] offset:3072 nt
	global_load_dwordx4 v[96:99], v22, s[88:89] nt
	global_load_dwordx4 v[100:103], v22, s[88:89] offset:1024 nt
	global_load_dwordx4 v[104:107], v22, s[88:89] offset:2048 nt
	global_load_dwordx4 v[108:111], v22, s[88:89] offset:3072 nt
	global_load_dwordx4 v[112:115], v23, s[88:89] nt
	global_load_dwordx4 v[116:119], v23, s[88:89] offset:1024 nt
	global_load_dwordx4 v[120:123], v23, s[88:89] offset:2048 nt
	global_load_dwordx4 v[124:127], v23, s[88:89] offset:3072 nt
	s_waitcnt vmcnt(15)
	global_store_dwordx4 v22, v[64:67], s[86:87] nt
	s_waitcnt vmcnt(15)
	global_store_dwordx4 v22, v[68:71], s[86:87] offset:1024 nt
	s_waitcnt vmcnt(15)
	global_store_dwordx4 v22, v[72:75], s[86:87] offset:2048 nt
	s_waitcnt vmcnt(15)
	global_store_dwordx4 v22, v[76:79], s[86:87] offset:3072 nt
	s_waitcnt vmcnt(15)
	global_store_dwordx4 v23, v[80:83], s[86:87] nt
	s_waitcnt vmcnt(15)
	global_store_dwordx4 v23, v[84:87], s[86:87] offset:1024 nt
	s_waitcnt vmcnt(15)
	global_store_dwordx4 v23, v[88:91], s[86:87] offset:2048 nt
	s_waitcnt vmcnt(15)
	global_store_dwordx4 v23, v[92:95], s[86:87] offset:3072 nt
	s_waitcnt vmcnt(15)
	global_store_dwordx4 v22, v[96:99], s[90:91] nt
	s_waitcnt vmcnt(15)
	global_store_dwordx4 v22, v[100:103], s[90:91] offset:1024 nt
	s_waitcnt vmcnt(15)
	global_store_dwordx4 v22, v[104:107], s[90:91] offset:2048 nt
	s_waitcnt vmcnt(15)
	global_store_dwordx4 v22, v[108:111], s[90:91] offset:3072 nt
	s_waitcnt vmcnt(15)
	global_store_dwordx4 v23, v[112:115], s[90:91] nt
	s_waitcnt vmcnt(15)
	global_store_dwordx4 v23, v[116:119], s[90:91] offset:1024 nt
	s_waitcnt vmcnt(15)
	global_store_dwordx4 v23, v[120:123], s[90:91] offset:2048 nt
	s_waitcnt vmcnt(15)
	global_store_dwordx4 v23, v[124:127], s[90:91] offset:3072 nt
	s_add_i32 s80, s101, s100
	s_branch .Lcpy2_loop
.Lcpy2_tail:
	s_cmp_lt_u32 s80, 0xbf40
	s_cbranch_scc0 .Lcpy2_end
	s_mul_hi_u32 s81, s80, 0x2ad5802b
	s_lshr_b32 s81, s81, 8
	s_mul_i32 s82, s81, 0x5fa
	s_sub_i32 s82, s80, s82
	s_lshl_b32 s82, s82, 13
	s_and_b32 s83, s81, 31
	s_mul_i32 s83, s83, 0xc00000
	s_add_i32 s82, s82, s83
	s_cmp_lt_u32 s81, 32
	s_cselect_b32 s84, s92, s94
	s_cselect_b32 s85, s93, s95
	s_mov_b32 s83, 0x1f210000
	s_cselect_b32 s83, 0x7210000, s83
	s_add_u32 s84, s84, s82
	s_addc_u32 s85, s85, 0
	s_add_u32 s84, s84, 0xc000
	s_addc_u32 s85, s85, 0
	s_add_u32 s83, s83, s82
	s_add_u32 s86, s98, s83
	s_addc_u32 s87, s99, 0
	global_load_dwordx4 v[64:67], v22, s[84:85] nt
	global_load_dwordx4 v[68:71], v22, s[84:85] offset:1024 nt
	global_load_dwordx4 v[72:75], v22, s[84:85] offset:2048 nt
	global_load_dwordx4 v[76:79], v22, s[84:85] offset:3072 nt
	global_load_dwordx4 v[80:83], v23, s[84:85] nt
	global_load_dwordx4 v[84:87], v23, s[84:85] offset:1024 nt
	global_load_dwordx4 v[88:91], v23, s[84:85] offset:2048 nt
	global_load_dwordx4 v[92:95], v23, s[84:85] offset:3072 nt
	s_waitcnt vmcnt(7)
	global_store_dwordx4 v22, v[64:67], s[86:87] nt
	s_waitcnt vmcnt(7)
	global_store_dwordx4 v22, v[68:71], s[86:87] offset:1024 nt
	s_waitcnt vmcnt(7)
	global_store_dwordx4 v22, v[72:75], s[86:87] offset:2048 nt
	s_waitcnt vmcnt(7)
	global_store_dwordx4 v22, v[76:79], s[86:87] offset:3072 nt
	s_waitcnt vmcnt(7)
	global_store_dwordx4 v23, v[80:83], s[86:87] nt
	s_waitcnt vmcnt(7)
	global_store_dwordx4 v23, v[84:87], s[86:87] offset:1024 nt
	s_waitcnt vmcnt(7)
	global_store_dwordx4 v23, v[88:91], s[86:87] offset:2048 nt
	s_waitcnt vmcnt(7)
	global_store_dwordx4 v23, v[92:95], s[86:87] offset:3072 nt

.LBB0_960:
	s_cmp_lt_u32 s33, 96
	s_cbranch_scc1 .Lcpyd_end
	s_cmp_ge_u32 s33, 848
	s_cbranch_scc1 .Lcpyd_end
	v_lshrrev_b32_e32 v21, 6, v174
	v_and_b32_e32 v22, 63, v174
	v_lshlrev_b32_e32 v22, 4, v22
	v_readfirstlane_b32 s80, v21
	v_add_u32_e32 v23, 0x1000, v22
	v_readfirstlane_b32 s92, v235
	v_readfirstlane_b32 s93, v236
	v_readfirstlane_b32 s94, v237
	v_readfirstlane_b32 s95, v238
	v_readfirstlane_b32 s98, v239
	v_readfirstlane_b32 s99, v240
	s_add_i32 s80, s80, s33
	s_add_i32 s80, s80, 0xbee0
	s_movk_i32 s100, 752
.Lcpyd_loop:
	s_add_i32 s101, s80, s100
	s_cmp_lt_u32 s101, 0xda98
	s_cbranch_scc0 .Lcpyd_tail
	s_mul_hi_u32 s81, s80, 0x2ad5802b
	s_lshr_b32 s81, s81, 8
	s_mul_i32 s82, s81, 0x5fa
	s_sub_i32 s82, s80, s82
	s_lshl_b32 s82, s82, 13
	s_and_b32 s83, s81, 31
	s_mul_i32 s83, s83, 0xc00000
	s_add_i32 s82, s82, s83
	s_cmp_lt_u32 s81, 32
	s_cselect_b32 s84, s92, s94
	s_cselect_b32 s85, s93, s95
	s_mov_b32 s83, 0x1f210000
	s_cselect_b32 s83, 0x7210000, s83
	s_add_u32 s84, s84, s82
	s_addc_u32 s85, s85, 0
	s_add_u32 s84, s84, 0xc000
	s_addc_u32 s85, s85, 0
	s_add_u32 s83, s83, s82
	s_add_u32 s86, s98, s83
	s_addc_u32 s87, s99, 0
	s_mul_hi_u32 s81, s101, 0x2ad5802b
	s_lshr_b32 s81, s81, 8
	s_mul_i32 s82, s81, 0x5fa
	s_sub_i32 s82, s101, s82
	s_lshl_b32 s82, s82, 13
	s_and_b32 s83, s81, 31
	s_mul_i32 s83, s83, 0xc00000
	s_add_i32 s82, s82, s83
	s_cmp_lt_u32 s81, 32
	s_cselect_b32 s88, s92, s94
	s_cselect_b32 s89, s93, s95
	s_mov_b32 s83, 0x1f210000
	s_cselect_b32 s83, 0x7210000, s83
	s_add_u32 s88, s88, s82
	s_addc_u32 s89, s89, 0
	s_add_u32 s88, s88, 0xc000
	s_addc_u32 s89, s89, 0
	s_add_u32 s83, s83, s82
	s_add_u32 s90, s98, s83
	s_addc_u32 s91, s99, 0
	global_load_dwordx4 v[64:67], v22, s[84:85] nt
	global_load_dwordx4 v[68:71], v22, s[84:85] offset:1024 nt
	global_load_dwordx4 v[72:75], v22, s[84:85] offset:2048 nt
	global_load_dwordx4 v[76:79], v22, s[84:85] offset:3072 nt
	global_load_dwordx4 v[80:83], v23, s[84:85] nt
	global_load_dwordx4 v[84:87], v23, s[84:85] offset:1024 nt
	global_load_dwordx4 v[88:91], v23, s[84:85] offset:2048 nt
	global_load_dwordx4 v[92:95], v23, s[84:85] offset:3072 nt
	global_load_dwordx4 v[96:99], v22, s[88:89] nt
	global_load_dwordx4 v[100:103], v22, s[88:89] offset:1024 nt
	global_load_dwordx4 v[104:107], v22, s[88:89] offset:2048 nt
	global_load_dwordx4 v[108:111], v22, s[88:89] offset:3072 nt
	global_load_dwordx4 v[112:115], v23, s[88:89] nt
	global_load_dwordx4 v[116:119], v23, s[88:89] offset:1024 nt
	global_load_dwordx4 v[120:123], v23, s[88:89] offset:2048 nt
	global_load_dwordx4 v[124:127], v23, s[88:89] offset:3072 nt
	s_waitcnt vmcnt(15)
	global_store_dwordx4 v22, v[64:67], s[86:87] nt
	s_waitcnt vmcnt(15)
	global_store_dwordx4 v22, v[68:71], s[86:87] offset:1024 nt
	s_waitcnt vmcnt(15)
	global_store_dwordx4 v22, v[72:75], s[86:87] offset:2048 nt
	s_waitcnt vmcnt(15)
	global_store_dwordx4 v22, v[76:79], s[86:87] offset:3072 nt
	s_waitcnt vmcnt(15)
	global_store_dwordx4 v23, v[80:83], s[86:87] nt
	s_waitcnt vmcnt(15)
	global_store_dwordx4 v23, v[84:87], s[86:87] offset:1024 nt
	s_waitcnt vmcnt(15)
	global_store_dwordx4 v23, v[88:91], s[86:87] offset:2048 nt
	s_waitcnt vmcnt(15)
	global_store_dwordx4 v23, v[92:95], s[86:87] offset:3072 nt
	s_waitcnt vmcnt(15)
	global_store_dwordx4 v22, v[96:99], s[90:91] nt
	s_waitcnt vmcnt(15)
	global_store_dwordx4 v22, v[100:103], s[90:91] offset:1024 nt
	s_waitcnt vmcnt(15)
	global_store_dwordx4 v22, v[104:107], s[90:91] offset:2048 nt
	s_waitcnt vmcnt(15)
	global_store_dwordx4 v22, v[108:111], s[90:91] offset:3072 nt
	s_waitcnt vmcnt(15)
	global_store_dwordx4 v23, v[112:115], s[90:91] nt
	s_waitcnt vmcnt(15)
	global_store_dwordx4 v23, v[116:119], s[90:91] offset:1024 nt
	s_waitcnt vmcnt(15)
	global_store_dwordx4 v23, v[120:123], s[90:91] offset:2048 nt
	s_waitcnt vmcnt(15)
	global_store_dwordx4 v23, v[124:127], s[90:91] offset:3072 nt
	s_add_i32 s80, s101, s100
	s_branch .Lcpyd_loop
.Lcpyd_tail:
	s_cmp_lt_u32 s80, 0xda98
	s_cbranch_scc0 .Lcpyd_end
	s_mul_hi_u32 s81, s80, 0x2ad5802b
	s_lshr_b32 s81, s81, 8
	s_mul_i32 s82, s81, 0x5fa
	s_sub_i32 s82, s80, s82
	s_lshl_b32 s82, s82, 13
	s_and_b32 s83, s81, 31
	s_mul_i32 s83, s83, 0xc00000
	s_add_i32 s82, s82, s83
	s_cmp_lt_u32 s81, 32
	s_cselect_b32 s84, s92, s94
	s_cselect_b32 s85, s93, s95
	s_mov_b32 s83, 0x1f210000
	s_cselect_b32 s83, 0x7210000, s83
	s_add_u32 s84, s84, s82
	s_addc_u32 s85, s85, 0
	s_add_u32 s84, s84, 0xc000
	s_addc_u32 s85, s85, 0
	s_add_u32 s83, s83, s82
	s_add_u32 s86, s98, s83
	s_addc_u32 s87, s99, 0
	global_load_dwordx4 v[64:67], v22, s[84:85] nt
	global_load_dwordx4 v[68:71], v22, s[84:85] offset:1024 nt
	global_load_dwordx4 v[72:75], v22, s[84:85] offset:2048 nt
	global_load_dwordx4 v[76:79], v22, s[84:85] offset:3072 nt
	global_load_dwordx4 v[80:83], v23, s[84:85] nt
	global_load_dwordx4 v[84:87], v23, s[84:85] offset:1024 nt
	global_load_dwordx4 v[88:91], v23, s[84:85] offset:2048 nt
	global_load_dwordx4 v[92:95], v23, s[84:85] offset:3072 nt
	s_waitcnt vmcnt(7)
	global_store_dwordx4 v22, v[64:67], s[86:87] nt
	s_waitcnt vmcnt(7)
	global_store_dwordx4 v22, v[68:71], s[86:87] offset:1024 nt
	s_waitcnt vmcnt(7)
	global_store_dwordx4 v22, v[72:75], s[86:87] offset:2048 nt
	s_waitcnt vmcnt(7)
	global_store_dwordx4 v22, v[76:79], s[86:87] offset:3072 nt
	s_waitcnt vmcnt(7)
	global_store_dwordx4 v23, v[80:83], s[86:87] nt
	s_waitcnt vmcnt(7)
	global_store_dwordx4 v23, v[84:87], s[86:87] offset:1024 nt
	s_waitcnt vmcnt(7)
	global_store_dwordx4 v23, v[88:91], s[86:87] offset:2048 nt
	s_waitcnt vmcnt(7)
	global_store_dwordx4 v23, v[92:95], s[86:87] offset:3072 nt

.LBB0_989:
	s_lshl_b32 s9, s9, 5
	s_mov_b64 s[16:17], 0x80
	s_and_b32 s14, s9, 0x60
	s_add_i32 m0, s34, 0x18000
	v_lshl_add_u64 v[6:7], v[6:7], 0, s[16:17]
	s_lshl_b32 s11, s8, 13
	s_lshl_b32 s9, s14, 7
	s_waitcnt vmcnt(4)
	s_barrier
	global_load_lds_dwordx4 v[6:7], off
	v_lshl_add_u64 v[4:5], v[4:5], 0, s[16:17]
	s_add_i32 m0, s34, 0x1a000
	s_add_i32 s47, s34, 0x8000
	s_add_i32 s54, s34, 0xa000
	global_load_lds_dwordx4 v[4:5], off
	v_lshl_add_u64 v[2:3], v[2:3], 0, s[16:17]
	s_mov_b32 m0, s47
	s_add_u32 s12, s26, 0xb0080
	global_load_lds_dwordx4 v[2:3], off
	v_lshl_add_u64 v[0:1], v[0:1], 0, s[16:17]
	s_mov_b32 m0, s54
	s_addc_u32 s13, s27, 0
	global_load_lds_dwordx4 v[0:1], off
	s_add_i32 m0, s34, 0x1c000
	v_lshl_add_u64 v[0:1], s[12:13], 0, v[130:131]
	global_load_lds_dwordx4 v[0:1], off
	v_lshl_add_u64 v[0:1], s[12:13], 0, v[134:135]
	s_add_i32 m0, s34, 0x1e000
	s_mov_b64 s[12:13], 0xb0080
	global_load_lds_dwordx4 v[0:1], off
	v_bfe_u32 v0, v8, 4, 2
	v_and_b32_e32 v1, 15, v8
	v_lshlrev_b32_e32 v2, 4, v0
	v_lshl_or_b32 v148, s8, 6, v1
	v_lshl_or_b32 v1, v1, 6, v2
	v_lshlrev_b32_e32 v2, 2, v8
	v_and_b32_e32 v2, 32, v2
	v_bitop3_b32 v3, v1, s11, v2 bitop3:0xde
	v_bitop3_b32 v149, v1, s9, v2 bitop3:0xde
	v_cmp_eq_u32_e64 s[8:9], 0, v0
	v_lshl_or_b32 v150, v0, 3, s14
	v_lshrrev_b32_e32 v1, 1, v9
	v_mul_lo_u32 v0, v11, s10
	s_mov_b32 s11, 0xb000
	v_mad_u64_u32 v[0:1], s[14:15], v1, s11, v[0:1]
	v_or_b32_e32 v0, v0, v10
	v_add_lshl_u32 v0, v0, v12, 1
	v_mov_b32_e32 v1, v131
	v_lshl_add_u64 v[136:137], v[0:1], 0, s[12:13]
	v_lshrrev_b32_e32 v1, 1, v13
	v_mul_lo_u32 v0, v14, s10
	v_mad_u64_u32 v[0:1], s[10:11], v1, s11, v[0:1]
	s_waitcnt vmcnt(6)
	v_or_b32_e32 v0, v0, v15
	v_add_lshl_u32 v0, v0, v16, 1
	v_mov_b32_e32 v1, v131
	s_add_i32 s57, 0, 0x10000
	s_add_i32 s58, 0, 0x14000
	s_bfe_i64 s[18:19], s[78:79], 0x200000
	s_ashr_i32 s55, s2, 31
	s_mov_b32 s56, s2
	v_lshl_add_u64 v[138:139], v[0:1], 0, s[12:13]
	v_mov_b64_e32 v[140:141], 0x100
	v_mov_b64_e32 v[142:143], 0xff
	v_add_u32_e32 v151, s57, v149
	v_add_u32_e32 v152, 0, v3
	v_add_u32_e32 v153, s58, v149
	v_mbcnt_hi_u32_b32 v154, -1, v175
	s_barrier
	s_branch .LBB0_991

.LBB0_1022:
	v_and_b32_e32 v160, 15, v174
	v_bfe_u32 v161, v174, 4, 2
	v_lshrrev_b32_e32 v162, 6, v174
	v_and_b32_e32 v136, 63, v174
	v_readfirstlane_b32 s80, v162
	s_lshr_b32 s81, s33, 8
	s_lshr_b32 s82, s33, 3
	s_and_b32 s82, s82, 31
	s_mul_i32 s83, s80, 704
	v_lshlrev_b32_e32 v164, 4, v161
	v_mov_b32_e32 v167, 0
	s_lshl_b32 s84, s82, 5
	v_add_u32_e32 v165, s84, v160
	v_mul_u32_u24_e32 v166, 0x1600, v165
	v_add3_u32 v166, v166, v164, s83
	s_add_u32 s86, s74, 0x3180000
	s_addc_u32 s87, s75, 0
	s_mov_b32 s88, 0x16000
	s_mov_b32 s89, 0
	v_lshl_add_u64 v[152:153], s[86:87], 0, v[166:167]
	v_lshl_add_u64 v[154:155], v[152:153], 0, s[88:89]
	s_lshl_b32 s84, s81, 5
	v_add_u32_e32 v165, s84, v160
	v_mul_u32_u24_e32 v166, 0x1600, v165
	v_add3_u32 v166, v166, v164, s83
	s_add_u32 s90, s74, 0x10980000
	s_addc_u32 s91, s75, 0
	v_lshl_add_u64 v[156:157], s[90:91], 0, v[166:167]
	v_lshl_add_u64 v[158:159], v[156:157], 0, s[88:89]
	v_mov_b32_e32 v128, 0
	v_mov_b32_e32 v129, 0
	v_mov_b32_e32 v130, 0
	v_mov_b32_e32 v131, 0
	v_mov_b32_e32 v132, 0
	v_mov_b32_e32 v133, 0
	v_mov_b32_e32 v134, 0
	v_mov_b32_e32 v135, 0
	v_mov_b32_e32 v144, 0
	v_mov_b32_e32 v145, 0
	v_mov_b32_e32 v146, 0
	v_mov_b32_e32 v147, 0
	v_mov_b32_e32 v148, 0
	v_mov_b32_e32 v149, 0
	v_mov_b32_e32 v150, 0
	v_mov_b32_e32 v151, 0
	global_load_dwordx4 v[0:3], v[152:153], off
	global_load_dwordx4 v[4:7], v[154:155], off
	global_load_dwordx4 v[8:11], v[156:157], off
	global_load_dwordx4 v[12:15], v[158:159], off
	global_load_dwordx4 v[16:19], v[152:153], off offset:64
	global_load_dwordx4 v[20:23], v[154:155], off offset:64
	global_load_dwordx4 v[24:27], v[156:157], off offset:64
	global_load_dwordx4 v[28:31], v[158:159], off offset:64
	global_load_dwordx4 v[32:35], v[152:153], off offset:128
	global_load_dwordx4 v[36:39], v[154:155], off offset:128
	global_load_dwordx4 v[40:43], v[156:157], off offset:128
	global_load_dwordx4 v[44:47], v[158:159], off offset:128
	global_load_dwordx4 v[48:51], v[152:153], off offset:192
	global_load_dwordx4 v[52:55], v[154:155], off offset:192
	global_load_dwordx4 v[56:59], v[156:157], off offset:192
	global_load_dwordx4 v[60:63], v[158:159], off offset:192
	global_load_dwordx4 v[64:67], v[152:153], off offset:256
	global_load_dwordx4 v[68:71], v[154:155], off offset:256
	global_load_dwordx4 v[72:75], v[156:157], off offset:256
	global_load_dwordx4 v[76:79], v[158:159], off offset:256
	global_load_dwordx4 v[80:83], v[152:153], off offset:320
	global_load_dwordx4 v[84:87], v[154:155], off offset:320
	global_load_dwordx4 v[88:91], v[156:157], off offset:320
	global_load_dwordx4 v[92:95], v[158:159], off offset:320
	global_load_dwordx4 v[96:99], v[152:153], off offset:384
	global_load_dwordx4 v[100:103], v[154:155], off offset:384
	global_load_dwordx4 v[104:107], v[156:157], off offset:384
	global_load_dwordx4 v[108:111], v[158:159], off offset:384
	global_load_dwordx4 v[112:115], v[152:153], off offset:448
	global_load_dwordx4 v[116:119], v[154:155], off offset:448
	global_load_dwordx4 v[120:123], v[156:157], off offset:448
	global_load_dwordx4 v[124:127], v[158:159], off offset:448
	s_waitcnt vmcnt(16)
	v_mfma_f32_16x16x32_bf16 v[128:131], v[0:3], v[8:11], v[128:131]
	v_mfma_f32_16x16x32_bf16 v[132:135], v[4:7], v[8:11], v[132:135]
	v_mfma_f32_16x16x32_bf16 v[144:147], v[0:3], v[12:15], v[144:147]
	v_mfma_f32_16x16x32_bf16 v[148:151], v[4:7], v[12:15], v[148:151]
	v_mfma_f32_16x16x32_bf16 v[128:131], v[16:19], v[24:27], v[128:131]
	v_mfma_f32_16x16x32_bf16 v[132:135], v[20:23], v[24:27], v[132:135]
	v_mfma_f32_16x16x32_bf16 v[144:147], v[16:19], v[28:31], v[144:147]
	v_mfma_f32_16x16x32_bf16 v[148:151], v[20:23], v[28:31], v[148:151]
	v_mfma_f32_16x16x32_bf16 v[128:131], v[32:35], v[40:43], v[128:131]
	v_mfma_f32_16x16x32_bf16 v[132:135], v[36:39], v[40:43], v[132:135]
	v_mfma_f32_16x16x32_bf16 v[144:147], v[32:35], v[44:47], v[144:147]
	v_mfma_f32_16x16x32_bf16 v[148:151], v[36:39], v[44:47], v[148:151]
	v_mfma_f32_16x16x32_bf16 v[128:131], v[48:51], v[56:59], v[128:131]
	v_mfma_f32_16x16x32_bf16 v[132:135], v[52:55], v[56:59], v[132:135]
	v_mfma_f32_16x16x32_bf16 v[144:147], v[48:51], v[60:63], v[144:147]
	v_mfma_f32_16x16x32_bf16 v[148:151], v[52:55], v[60:63], v[148:151]
	global_load_dwordx4 v[0:3], v[152:153], off offset:512
	global_load_dwordx4 v[4:7], v[154:155], off offset:512
	global_load_dwordx4 v[8:11], v[156:157], off offset:512
	global_load_dwordx4 v[12:15], v[158:159], off offset:512
	global_load_dwordx4 v[16:19], v[152:153], off offset:576
	global_load_dwordx4 v[20:23], v[154:155], off offset:576
	global_load_dwordx4 v[24:27], v[156:157], off offset:576
	global_load_dwordx4 v[28:31], v[158:159], off offset:576
	global_load_dwordx4 v[32:35], v[152:153], off offset:640
	global_load_dwordx4 v[36:39], v[154:155], off offset:640
	global_load_dwordx4 v[40:43], v[156:157], off offset:640
	global_load_dwordx4 v[44:47], v[158:159], off offset:640
	s_waitcnt vmcnt(12)
	v_mfma_f32_16x16x32_bf16 v[128:131], v[64:67], v[72:75], v[128:131]
	v_mfma_f32_16x16x32_bf16 v[132:135], v[68:71], v[72:75], v[132:135]
	v_mfma_f32_16x16x32_bf16 v[144:147], v[64:67], v[76:79], v[144:147]
	v_mfma_f32_16x16x32_bf16 v[148:151], v[68:71], v[76:79], v[148:151]
	v_mfma_f32_16x16x32_bf16 v[128:131], v[80:83], v[88:91], v[128:131]
	v_mfma_f32_16x16x32_bf16 v[132:135], v[84:87], v[88:91], v[132:135]
	v_mfma_f32_16x16x32_bf16 v[144:147], v[80:83], v[92:95], v[144:147]
	v_mfma_f32_16x16x32_bf16 v[148:151], v[84:87], v[92:95], v[148:151]
	v_mfma_f32_16x16x32_bf16 v[128:131], v[96:99], v[104:107], v[128:131]
	v_mfma_f32_16x16x32_bf16 v[132:135], v[100:103], v[104:107], v[132:135]
	v_mfma_f32_16x16x32_bf16 v[144:147], v[96:99], v[108:111], v[144:147]
	v_mfma_f32_16x16x32_bf16 v[148:151], v[100:103], v[108:111], v[148:151]
	v_mfma_f32_16x16x32_bf16 v[128:131], v[112:115], v[120:123], v[128:131]
	v_mfma_f32_16x16x32_bf16 v[132:135], v[116:119], v[120:123], v[132:135]
	v_mfma_f32_16x16x32_bf16 v[144:147], v[112:115], v[124:127], v[144:147]
	v_mfma_f32_16x16x32_bf16 v[148:151], v[116:119], v[124:127], v[148:151]
	s_waitcnt vmcnt(0)
	v_mfma_f32_16x16x32_bf16 v[128:131], v[0:3], v[8:11], v[128:131]
	v_mfma_f32_16x16x32_bf16 v[132:135], v[4:7], v[8:11], v[132:135]
	v_mfma_f32_16x16x32_bf16 v[144:147], v[0:3], v[12:15], v[144:147]
	v_mfma_f32_16x16x32_bf16 v[148:151], v[4:7], v[12:15], v[148:151]
	v_mfma_f32_16x16x32_bf16 v[128:131], v[16:19], v[24:27], v[128:131]
	v_mfma_f32_16x16x32_bf16 v[132:135], v[20:23], v[24:27], v[132:135]
	v_mfma_f32_16x16x32_bf16 v[144:147], v[16:19], v[28:31], v[144:147]
	v_mfma_f32_16x16x32_bf16 v[148:151], v[20:23], v[28:31], v[148:151]
	v_mfma_f32_16x16x32_bf16 v[128:131], v[32:35], v[40:43], v[128:131]
	v_mfma_f32_16x16x32_bf16 v[132:135], v[36:39], v[40:43], v[132:135]
	v_mfma_f32_16x16x32_bf16 v[144:147], v[32:35], v[44:47], v[144:147]
	v_mfma_f32_16x16x32_bf16 v[148:151], v[36:39], v[44:47], v[148:151]
	s_nop 7
	s_nop 7
	v_lshlrev_b32_e32 v170, 12, v162
	v_lshl_add_u32 v170, v136, 4, v170
	ds_write_b128 v170, v[128:131]
	ds_write_b128 v170, v[132:135] offset:1024
	ds_write_b128 v170, v[144:147] offset:2048
	ds_write_b128 v170, v[148:151] offset:3072
	s_waitcnt lgkmcnt(0)
	s_barrier
	s_cmp_ge_u32 s80, 4
	s_cbranch_scc1 .Lmg3_end
	s_lshl_b32 s84, s80, 10
	v_lshlrev_b32_e32 v171, 4, v136
	v_add_u32_e32 v171, s84, v171
	ds_read_b128 v[0:3], v171
	ds_read_b128 v[4:7], v171 offset:4096
	ds_read_b128 v[8:11], v171 offset:8192
	ds_read_b128 v[12:15], v171 offset:12288
	ds_read_b128 v[16:19], v171 offset:16384
	ds_read_b128 v[20:23], v171 offset:20480
	ds_read_b128 v[24:27], v171 offset:24576
	ds_read_b128 v[28:31], v171 offset:28672
	s_lshr_b32 s84, s80, 1
	s_lshl_b32 s84, s84, 4
	s_lshl_b32 s85, s81, 5
	s_add_i32 s84, s84, s85
	s_addk_i32 s84, 0x4000
	s_and_b32 s85, s80, 1
	s_lshl_b32 s85, s85, 4
	s_lshl_b32 s83, s82, 5
	s_add_i32 s85, s85, s83
	v_add_u32_e32 v165, s84, v160
	v_lshl_add_u32 v164, v161, 2, s85
	v_lshlrev_b32_e32 v166, 12, v165
	v_lshl_add_u32 v166, v164, 2, v166
	v_mov_b32_e32 v167, 0
	s_add_u32 s86, s74, 0x5000000
	s_addc_u32 s87, s75, 0
	v_lshl_add_u64 v[168:169], s[86:87], 0, v[166:167]
	global_load_dwordx4 v[32:35], v[168:169], off
	v_lshrrev_b32_e32 v172, 1, v166
	v_mov_b32_e32 v173, 0
	s_add_u32 s86, s74, 0x9100000
	s_addc_u32 s87, s75, 0
	v_lshl_add_u64 v[172:173], s[86:87], 0, v[172:173]
	v_lshlrev_b32_e32 v166, 2, v165
	s_add_u32 s86, s74, 0x12ba1000
	s_addc_u32 s87, s75, 0
	v_lshl_add_u64 v[166:167], s[86:87], 0, v[166:167]
	s_waitcnt lgkmcnt(0)
	v_add_f32_e32 v0, v0, v4
	v_add_f32_e32 v1, v1, v5
	v_add_f32_e32 v2, v2, v6
	v_add_f32_e32 v3, v3, v7
	v_add_f32_e32 v0, v0, v8
	v_add_f32_e32 v1, v1, v9
	v_add_f32_e32 v2, v2, v10
	v_add_f32_e32 v3, v3, v11
	v_add_f32_e32 v0, v0, v12
	v_add_f32_e32 v1, v1, v13
	v_add_f32_e32 v2, v2, v14
	v_add_f32_e32 v3, v3, v15
	v_add_f32_e32 v0, v0, v16
	v_add_f32_e32 v1, v1, v17
	v_add_f32_e32 v2, v2, v18
	v_add_f32_e32 v3, v3, v19
	v_add_f32_e32 v0, v0, v20
	v_add_f32_e32 v1, v1, v21
	v_add_f32_e32 v2, v2, v22
	v_add_f32_e32 v3, v3, v23
	v_add_f32_e32 v0, v0, v24
	v_add_f32_e32 v1, v1, v25
	v_add_f32_e32 v2, v2, v26
	v_add_f32_e32 v3, v3, v27
	v_add_f32_e32 v0, v0, v28
	v_add_f32_e32 v1, v1, v29
	v_add_f32_e32 v2, v2, v30
	v_add_f32_e32 v3, v3, v31
	s_waitcnt vmcnt(0)
	v_fma_f32 v32, v0, 0.5, v32
	v_fma_f32 v33, v1, 0.5, v33
	v_fma_f32 v34, v2, 0.5, v34
	v_fma_f32 v35, v3, 0.5, v35
	global_store_dwordx4 v[168:169], v[32:35], off
	v_cvt_pk_bf16_f32 v36, v32, v33
	v_cvt_pk_bf16_f32 v37, v34, v35
	global_store_dwordx2 v[172:173], v[36:37], off
	v_mul_f32_e32 v38, v32, v32
	v_fmac_f32_e32 v38, v33, v33
	v_fmac_f32_e32 v38, v34, v34
	v_fmac_f32_e32 v38, v35, v35
	v_xor_b32_e32 v39, 16, v136
	v_lshlrev_b32_e32 v39, 2, v39
	ds_bpermute_b32 v40, v39, v38
	v_xor_b32_e32 v41, 32, v136
	v_lshlrev_b32_e32 v41, 2, v41
	s_waitcnt lgkmcnt(0)
	v_add_f32_e32 v38, v38, v40
	ds_bpermute_b32 v40, v41, v38
	s_waitcnt lgkmcnt(0)
	v_add_f32_e32 v38, v38, v40
	v_cmp_gt_u32_e64 s[82:83], 16, v136
	s_nop 1
	s_and_saveexec_b64 s[84:85], s[82:83]
	global_atomic_add_f32 v[166:167], v38, off
	s_mov_b64 exec, s[84:85]
.Lmg3_end:
	s_cmp_lt_u32 s33, 32
	s_cbranch_scc1 .Lcpy3_end
	v_lshrrev_b32_e32 v21, 6, v174
	v_and_b32_e32 v22, 63, v174
	v_lshlrev_b32_e32 v22, 4, v22
	v_readfirstlane_b32 s80, v21
	v_add_u32_e32 v23, 0x1000, v22
	v_readfirstlane_b32 s92, v235
	v_readfirstlane_b32 s93, v236
	v_readfirstlane_b32 s94, v237
	v_readfirstlane_b32 s95, v238
	v_readfirstlane_b32 s98, v239
	v_readfirstlane_b32 s99, v240
	s_add_i32 s80, s80, s33
	s_add_i32 s80, s80, 0xda78
	s_sub_i32 s100, s78, 4
	s_lshl_b32 s100, s100, 3
.Lcpy3_loop:
	s_add_i32 s101, s80, s100
	s_cmp_lt_u32 s101, 0x10388
	s_cbranch_scc0 .Lcpy3_tail
	s_mul_hi_u32 s81, s80, 0x2ad5802b
	s_lshr_b32 s81, s81, 8
	s_mul_i32 s82, s81, 0x5fa
	s_sub_i32 s82, s80, s82
	s_lshl_b32 s82, s82, 13
	s_and_b32 s83, s81, 31
	s_mul_i32 s83, s83, 0xc00000
	s_add_i32 s82, s82, s83
	s_cmp_lt_u32 s81, 32
	s_cselect_b32 s84, s92, s94
	s_cselect_b32 s85, s93, s95
	s_mov_b32 s83, 0x1f210000
	s_cselect_b32 s83, 0x7210000, s83
	s_add_u32 s84, s84, s82
	s_addc_u32 s85, s85, 0
	s_add_u32 s84, s84, 0xc000
	s_addc_u32 s85, s85, 0
	s_add_u32 s83, s83, s82
	s_add_u32 s86, s98, s83
	s_addc_u32 s87, s99, 0
	s_mul_hi_u32 s81, s101, 0x2ad5802b
	s_lshr_b32 s81, s81, 8
	s_mul_i32 s82, s81, 0x5fa
	s_sub_i32 s82, s101, s82
	s_lshl_b32 s82, s82, 13
	s_and_b32 s83, s81, 31
	s_mul_i32 s83, s83, 0xc00000
	s_add_i32 s82, s82, s83
	s_cmp_lt_u32 s81, 32
	s_cselect_b32 s88, s92, s94
	s_cselect_b32 s89, s93, s95
	s_mov_b32 s83, 0x1f210000
	s_cselect_b32 s83, 0x7210000, s83
	s_add_u32 s88, s88, s82
	s_addc_u32 s89, s89, 0
	s_add_u32 s88, s88, 0xc000
	s_addc_u32 s89, s89, 0
	s_add_u32 s83, s83, s82
	s_add_u32 s90, s98, s83
	s_addc_u32 s91, s99, 0
	global_load_dwordx4 v[64:67], v22, s[84:85] nt
	global_load_dwordx4 v[68:71], v22, s[84:85] offset:1024 nt
	global_load_dwordx4 v[72:75], v22, s[84:85] offset:2048 nt
	global_load_dwordx4 v[76:79], v22, s[84:85] offset:3072 nt
	global_load_dwordx4 v[80:83], v23, s[84:85] nt
	global_load_dwordx4 v[84:87], v23, s[84:85] offset:1024 nt
	global_load_dwordx4 v[88:91], v23, s[84:85] offset:2048 nt
	global_load_dwordx4 v[92:95], v23, s[84:85] offset:3072 nt
	global_load_dwordx4 v[96:99], v22, s[88:89] nt
	global_load_dwordx4 v[100:103], v22, s[88:89] offset:1024 nt
	global_load_dwordx4 v[104:107], v22, s[88:89] offset:2048 nt
	global_load_dwordx4 v[108:111], v22, s[88:89] offset:3072 nt
	global_load_dwordx4 v[112:115], v23, s[88:89] nt
	global_load_dwordx4 v[116:119], v23, s[88:89] offset:1024 nt
	global_load_dwordx4 v[120:123], v23, s[88:89] offset:2048 nt
	global_load_dwordx4 v[124:127], v23, s[88:89] offset:3072 nt
	s_waitcnt vmcnt(15)
	global_store_dwordx4 v22, v[64:67], s[86:87] nt
	s_waitcnt vmcnt(15)
	global_store_dwordx4 v22, v[68:71], s[86:87] offset:1024 nt
	s_waitcnt vmcnt(15)
	global_store_dwordx4 v22, v[72:75], s[86:87] offset:2048 nt
	s_waitcnt vmcnt(15)
	global_store_dwordx4 v22, v[76:79], s[86:87] offset:3072 nt
	s_waitcnt vmcnt(15)
	global_store_dwordx4 v23, v[80:83], s[86:87] nt
	s_waitcnt vmcnt(15)
	global_store_dwordx4 v23, v[84:87], s[86:87] offset:1024 nt
	s_waitcnt vmcnt(15)
	global_store_dwordx4 v23, v[88:91], s[86:87] offset:2048 nt
	s_waitcnt vmcnt(15)
	global_store_dwordx4 v23, v[92:95], s[86:87] offset:3072 nt
	s_waitcnt vmcnt(15)
	global_store_dwordx4 v22, v[96:99], s[90:91] nt
	s_waitcnt vmcnt(15)
	global_store_dwordx4 v22, v[100:103], s[90:91] offset:1024 nt
	s_waitcnt vmcnt(15)
	global_store_dwordx4 v22, v[104:107], s[90:91] offset:2048 nt
	s_waitcnt vmcnt(15)
	global_store_dwordx4 v22, v[108:111], s[90:91] offset:3072 nt
	s_waitcnt vmcnt(15)
	global_store_dwordx4 v23, v[112:115], s[90:91] nt
	s_waitcnt vmcnt(15)
	global_store_dwordx4 v23, v[116:119], s[90:91] offset:1024 nt
	s_waitcnt vmcnt(15)
	global_store_dwordx4 v23, v[120:123], s[90:91] offset:2048 nt
	s_waitcnt vmcnt(15)
	global_store_dwordx4 v23, v[124:127], s[90:91] offset:3072 nt
	s_add_i32 s80, s101, s100
	s_branch .Lcpy3_loop
.Lcpy3_tail:
	s_cmp_lt_u32 s80, 0x10388
	s_cbranch_scc0 .Lcpy3_end
	s_mul_hi_u32 s81, s80, 0x2ad5802b
	s_lshr_b32 s81, s81, 8
	s_mul_i32 s82, s81, 0x5fa
	s_sub_i32 s82, s80, s82
	s_lshl_b32 s82, s82, 13
	s_and_b32 s83, s81, 31
	s_mul_i32 s83, s83, 0xc00000
	s_add_i32 s82, s82, s83
	s_cmp_lt_u32 s81, 32
	s_cselect_b32 s84, s92, s94
	s_cselect_b32 s85, s93, s95
	s_mov_b32 s83, 0x1f210000
	s_cselect_b32 s83, 0x7210000, s83
	s_add_u32 s84, s84, s82
	s_addc_u32 s85, s85, 0
	s_add_u32 s84, s84, 0xc000
	s_addc_u32 s85, s85, 0
	s_add_u32 s83, s83, s82
	s_add_u32 s86, s98, s83
	s_addc_u32 s87, s99, 0
	global_load_dwordx4 v[64:67], v22, s[84:85] nt
	global_load_dwordx4 v[68:71], v22, s[84:85] offset:1024 nt
	global_load_dwordx4 v[72:75], v22, s[84:85] offset:2048 nt
	global_load_dwordx4 v[76:79], v22, s[84:85] offset:3072 nt
	global_load_dwordx4 v[80:83], v23, s[84:85] nt
	global_load_dwordx4 v[84:87], v23, s[84:85] offset:1024 nt
	global_load_dwordx4 v[88:91], v23, s[84:85] offset:2048 nt
	global_load_dwordx4 v[92:95], v23, s[84:85] offset:3072 nt
	s_waitcnt vmcnt(7)
	global_store_dwordx4 v22, v[64:67], s[86:87] nt
	s_waitcnt vmcnt(7)
	global_store_dwordx4 v22, v[68:71], s[86:87] offset:1024 nt
	s_waitcnt vmcnt(7)
	global_store_dwordx4 v22, v[72:75], s[86:87] offset:2048 nt
	s_waitcnt vmcnt(7)
	global_store_dwordx4 v22, v[76:79], s[86:87] offset:3072 nt
	s_waitcnt vmcnt(7)
	global_store_dwordx4 v23, v[80:83], s[86:87] nt
	s_waitcnt vmcnt(7)
	global_store_dwordx4 v23, v[84:87], s[86:87] offset:1024 nt
	s_waitcnt vmcnt(7)
	global_store_dwordx4 v23, v[88:91], s[86:87] offset:2048 nt
	s_waitcnt vmcnt(7)
	global_store_dwordx4 v23, v[92:95], s[86:87] offset:3072 nt

.LBB0_1288:
	s_cmp_lt_u32 s33, 1072
	s_cbranch_scc1 .Lcpye_end
	v_lshrrev_b32_e32 v21, 6, v174
	v_and_b32_e32 v22, 63, v174
	v_lshlrev_b32_e32 v22, 4, v22
	v_readfirstlane_b32 s80, v21
	v_add_u32_e32 v23, 0x1000, v22
	v_readfirstlane_b32 s92, v235
	v_readfirstlane_b32 s93, v236
	v_readfirstlane_b32 s94, v237
	v_readfirstlane_b32 s95, v238
	v_readfirstlane_b32 s98, v239
	v_readfirstlane_b32 s99, v240
	s_add_i32 s80, s80, s33
	s_add_i32 s80, s80, 0xff58
	s_sub_i32 s100, s78, 134
	s_lshl_b32 s100, s100, 3
.Lcpye_loop:
	s_add_i32 s101, s80, s100
	s_cmp_lt_u32 s101, 0x122c8
	s_cbranch_scc0 .Lcpye_tail
	s_mul_hi_u32 s81, s80, 0x2ad5802b
	s_lshr_b32 s81, s81, 8
	s_mul_i32 s82, s81, 0x5fa
	s_sub_i32 s82, s80, s82
	s_lshl_b32 s82, s82, 13
	s_and_b32 s83, s81, 31
	s_mul_i32 s83, s83, 0xc00000
	s_add_i32 s82, s82, s83
	s_cmp_lt_u32 s81, 32
	s_cselect_b32 s84, s92, s94
	s_cselect_b32 s85, s93, s95
	s_mov_b32 s83, 0x1f210000
	s_cselect_b32 s83, 0x7210000, s83
	s_add_u32 s84, s84, s82
	s_addc_u32 s85, s85, 0
	s_add_u32 s84, s84, 0xc000
	s_addc_u32 s85, s85, 0
	s_add_u32 s83, s83, s82
	s_add_u32 s86, s98, s83
	s_addc_u32 s87, s99, 0
	s_mul_hi_u32 s81, s101, 0x2ad5802b
	s_lshr_b32 s81, s81, 8
	s_mul_i32 s82, s81, 0x5fa
	s_sub_i32 s82, s101, s82
	s_lshl_b32 s82, s82, 13
	s_and_b32 s83, s81, 31
	s_mul_i32 s83, s83, 0xc00000
	s_add_i32 s82, s82, s83
	s_cmp_lt_u32 s81, 32
	s_cselect_b32 s88, s92, s94
	s_cselect_b32 s89, s93, s95
	s_mov_b32 s83, 0x1f210000
	s_cselect_b32 s83, 0x7210000, s83
	s_add_u32 s88, s88, s82
	s_addc_u32 s89, s89, 0
	s_add_u32 s88, s88, 0xc000
	s_addc_u32 s89, s89, 0
	s_add_u32 s83, s83, s82
	s_add_u32 s90, s98, s83
	s_addc_u32 s91, s99, 0
	global_load_dwordx4 v[64:67], v22, s[84:85] nt
	global_load_dwordx4 v[68:71], v22, s[84:85] offset:1024 nt
	global_load_dwordx4 v[72:75], v22, s[84:85] offset:2048 nt
	global_load_dwordx4 v[76:79], v22, s[84:85] offset:3072 nt
	global_load_dwordx4 v[80:83], v23, s[84:85] nt
	global_load_dwordx4 v[84:87], v23, s[84:85] offset:1024 nt
	global_load_dwordx4 v[88:91], v23, s[84:85] offset:2048 nt
	global_load_dwordx4 v[92:95], v23, s[84:85] offset:3072 nt
	global_load_dwordx4 v[96:99], v22, s[88:89] nt
	global_load_dwordx4 v[100:103], v22, s[88:89] offset:1024 nt
	global_load_dwordx4 v[104:107], v22, s[88:89] offset:2048 nt
	global_load_dwordx4 v[108:111], v22, s[88:89] offset:3072 nt
	global_load_dwordx4 v[112:115], v23, s[88:89] nt
	global_load_dwordx4 v[116:119], v23, s[88:89] offset:1024 nt
	global_load_dwordx4 v[120:123], v23, s[88:89] offset:2048 nt
	global_load_dwordx4 v[124:127], v23, s[88:89] offset:3072 nt
	s_waitcnt vmcnt(15)
	global_store_dwordx4 v22, v[64:67], s[86:87] nt
	s_waitcnt vmcnt(15)
	global_store_dwordx4 v22, v[68:71], s[86:87] offset:1024 nt
	s_waitcnt vmcnt(15)
	global_store_dwordx4 v22, v[72:75], s[86:87] offset:2048 nt
	s_waitcnt vmcnt(15)
	global_store_dwordx4 v22, v[76:79], s[86:87] offset:3072 nt
	s_waitcnt vmcnt(15)
	global_store_dwordx4 v23, v[80:83], s[86:87] nt
	s_waitcnt vmcnt(15)
	global_store_dwordx4 v23, v[84:87], s[86:87] offset:1024 nt
	s_waitcnt vmcnt(15)
	global_store_dwordx4 v23, v[88:91], s[86:87] offset:2048 nt
	s_waitcnt vmcnt(15)
	global_store_dwordx4 v23, v[92:95], s[86:87] offset:3072 nt
	s_waitcnt vmcnt(15)
	global_store_dwordx4 v22, v[96:99], s[90:91] nt
	s_waitcnt vmcnt(15)
	global_store_dwordx4 v22, v[100:103], s[90:91] offset:1024 nt
	s_waitcnt vmcnt(15)
	global_store_dwordx4 v22, v[104:107], s[90:91] offset:2048 nt
	s_waitcnt vmcnt(15)
	global_store_dwordx4 v22, v[108:111], s[90:91] offset:3072 nt
	s_waitcnt vmcnt(15)
	global_store_dwordx4 v23, v[112:115], s[90:91] nt
	s_waitcnt vmcnt(15)
	global_store_dwordx4 v23, v[116:119], s[90:91] offset:1024 nt
	s_waitcnt vmcnt(15)
	global_store_dwordx4 v23, v[120:123], s[90:91] offset:2048 nt
	s_waitcnt vmcnt(15)
	global_store_dwordx4 v23, v[124:127], s[90:91] offset:3072 nt
	s_add_i32 s80, s101, s100
	s_branch .Lcpye_loop
.Lcpye_tail:
	s_cmp_lt_u32 s80, 0x122c8
	s_cbranch_scc0 .Lcpye_end
	s_mul_hi_u32 s81, s80, 0x2ad5802b
	s_lshr_b32 s81, s81, 8
	s_mul_i32 s82, s81, 0x5fa
	s_sub_i32 s82, s80, s82
	s_lshl_b32 s82, s82, 13
	s_and_b32 s83, s81, 31
	s_mul_i32 s83, s83, 0xc00000
	s_add_i32 s82, s82, s83
	s_cmp_lt_u32 s81, 32
	s_cselect_b32 s84, s92, s94
	s_cselect_b32 s85, s93, s95
	s_mov_b32 s83, 0x1f210000
	s_cselect_b32 s83, 0x7210000, s83
	s_add_u32 s84, s84, s82
	s_addc_u32 s85, s85, 0
	s_add_u32 s84, s84, 0xc000
	s_addc_u32 s85, s85, 0
	s_add_u32 s83, s83, s82
	s_add_u32 s86, s98, s83
	s_addc_u32 s87, s99, 0
	global_load_dwordx4 v[64:67], v22, s[84:85] nt
	global_load_dwordx4 v[68:71], v22, s[84:85] offset:1024 nt
	global_load_dwordx4 v[72:75], v22, s[84:85] offset:2048 nt
	global_load_dwordx4 v[76:79], v22, s[84:85] offset:3072 nt
	global_load_dwordx4 v[80:83], v23, s[84:85] nt
	global_load_dwordx4 v[84:87], v23, s[84:85] offset:1024 nt
	global_load_dwordx4 v[88:91], v23, s[84:85] offset:2048 nt
	global_load_dwordx4 v[92:95], v23, s[84:85] offset:3072 nt
	s_waitcnt vmcnt(7)
	global_store_dwordx4 v22, v[64:67], s[86:87] nt
	s_waitcnt vmcnt(7)
	global_store_dwordx4 v22, v[68:71], s[86:87] offset:1024 nt
	s_waitcnt vmcnt(7)
	global_store_dwordx4 v22, v[72:75], s[86:87] offset:2048 nt
	s_waitcnt vmcnt(7)
	global_store_dwordx4 v22, v[76:79], s[86:87] offset:3072 nt
	s_waitcnt vmcnt(7)
	global_store_dwordx4 v23, v[80:83], s[86:87] nt
	s_waitcnt vmcnt(7)
	global_store_dwordx4 v23, v[84:87], s[86:87] offset:1024 nt
	s_waitcnt vmcnt(7)
	global_store_dwordx4 v23, v[88:91], s[86:87] offset:2048 nt
	s_waitcnt vmcnt(7)
	global_store_dwordx4 v23, v[92:95], s[86:87] offset:3072 nt

.LBB0_1383:
	s_or_b64 exec, exec, s[8:9]
	v_readlane_b32 s4, v234, 2
	v_mov_b32_e32 v8, v174
	v_readlane_b32 s5, v234, 3
	s_barrier
	s_and_b64 vcc, exec, s[4:5]
	v_readfirstlane_b32 s3, v8
	s_cbranch_vccnz .LBB0_1389
	s_ashr_i32 s4, s2, 31
	s_lshr_b32 s4, s4, 29
	s_add_i32 s4, s2, s4
	s_and_b32 s5, s4, -8
	s_sub_i32 s5, s2, s5
	s_cmp_gt_i32 s5, -1
	s_cbranch_scc0 .LBB0_1386
	s_lshl_b32 s6, s5, 5
	s_or_b32 s6, s6, 0
	s_cbranch_execz .LBB0_1387
	s_branch .LBB0_1388

.LBB0_1392:
	s_lshl_b32 s9, s9, 5
	s_mov_b64 s[16:17], 0x80
	s_and_b32 s20, s9, 0x60
	s_add_i32 m0, s7, 0x18000
	v_lshl_add_u64 v[6:7], v[6:7], 0, s[16:17]
	s_lshl_b32 s18, s8, 13
	s_lshl_b32 s9, s20, 7
	s_waitcnt vmcnt(4)
	s_barrier
	global_load_lds_dwordx4 v[6:7], off
	v_lshl_add_u64 v[4:5], v[4:5], 0, s[16:17]
	s_add_i32 m0, s7, 0x1a000
	s_add_i32 s49, s7, 0x8000
	s_add_i32 s50, s7, 0xa000
	global_load_lds_dwordx4 v[4:5], off
	v_lshl_add_u64 v[2:3], v[2:3], 0, s[16:17]
	s_mov_b32 m0, s49
	s_add_u32 s10, s36, 0x20080
	global_load_lds_dwordx4 v[2:3], off
	v_lshl_add_u64 v[0:1], v[0:1], 0, s[16:17]
	s_mov_b32 m0, s50
	s_addc_u32 s11, s37, 0
	global_load_lds_dwordx4 v[0:1], off
	s_add_i32 m0, s7, 0x1c000
	v_lshl_add_u64 v[0:1], s[10:11], 0, v[130:131]
	global_load_lds_dwordx4 v[0:1], off
	v_lshl_add_u64 v[0:1], s[10:11], 0, v[134:135]
	s_add_i32 m0, s7, 0x1e000
	s_add_i32 s52, 0, 0x10000
	global_load_lds_dwordx4 v[0:1], off
	v_bfe_u32 v0, v8, 4, 2
	v_and_b32_e32 v1, 15, v8
	v_lshlrev_b32_e32 v2, 4, v0
	v_lshl_or_b32 v148, s8, 6, v1
	v_lshl_or_b32 v1, v1, 6, v2
	v_lshlrev_b32_e32 v2, 2, v8
	v_and_b32_e32 v2, 32, v2
	v_bitop3_b32 v149, v1, s9, v2 bitop3:0xde
	v_cmp_eq_u32_e64 s[8:9], 0, v0
	v_lshl_or_b32 v150, v0, 3, s20
	v_lshlrev_b32_e32 v0, 13, v9
	v_and_b32_e32 v0, 0xffffc000, v0
	v_bitop3_b32 v3, v1, s18, v2 bitop3:0xde
	v_lshl_add_u32 v0, v10, 10, v0
	v_and_b32_e32 v1, 1, v9
	v_lshl_or_b32 v0, v1, 6, v0
	v_lshl_add_u32 v136, v11, 1, v0
	v_lshlrev_b32_e32 v0, 13, v12
	v_and_b32_e32 v0, 0xffffc000, v0
	s_waitcnt vmcnt(6)
	v_lshl_add_u32 v0, v13, 10, v0
	v_and_b32_e32 v1, 1, v12
	v_lshl_or_b32 v0, v1, 6, v0
	s_add_i32 s53, 0, 0x14000
	s_bfe_i64 s[18:19], s[78:79], 0x200000
	s_ashr_i32 s51, s2, 31
	v_mov_b32_e32 v137, v131
	v_lshl_add_u32 v138, v14, 1, v0
	v_mov_b32_e32 v139, v131
	v_mov_b64_e32 v[140:141], 0x100
	v_mov_b64_e32 v[142:143], 0xff
	v_add_u32_e32 v151, s52, v149
	v_add_u32_e32 v152, 0, v3
	v_add_u32_e32 v153, s53, v149
	v_mbcnt_hi_u32_b32 v154, -1, v175
	s_barrier
	s_branch .LBB0_1394

.LBB0_1421:
	v_and_b32_e32 v160, 15, v174
	v_bfe_u32 v161, v174, 4, 2
	v_lshrrev_b32_e32 v162, 6, v174
	v_and_b32_e32 v136, 63, v174
	v_readfirstlane_b32 s80, v162
	s_lshr_b32 s81, s33, 8
	s_lshr_b32 s82, s33, 3
	s_and_b32 s82, s82, 31
	s_mul_i32 s83, s80, 128
	v_lshlrev_b32_e32 v164, 4, v161
	v_mov_b32_e32 v167, 0
	s_lshl_b32 s84, s82, 5
	v_add_u32_e32 v165, s84, v160
	v_mul_u32_u24_e32 v166, 0x400, v165
	v_add3_u32 v166, v166, v164, s83
	s_add_u32 s86, s74, 0x4f00000
	s_addc_u32 s87, s75, 0
	s_mov_b32 s88, 0x4000
	s_mov_b32 s89, 0
	v_lshl_add_u64 v[152:153], s[86:87], 0, v[166:167]
	v_lshl_add_u64 v[154:155], v[152:153], 0, s[88:89]
	s_lshl_b32 s84, s81, 5
	v_add_u32_e32 v165, s84, v160
	v_mul_u32_u24_e32 v166, 0x400, v165
	v_add3_u32 v166, v166, v164, s83
	s_add_u32 s90, s74, 0x3d16bc00
	s_addc_u32 s91, s75, 0
	v_lshl_add_u64 v[156:157], s[90:91], 0, v[166:167]
	v_lshl_add_u64 v[158:159], v[156:157], 0, s[88:89]
	v_mov_b32_e32 v128, 0
	v_mov_b32_e32 v129, 0
	v_mov_b32_e32 v130, 0
	v_mov_b32_e32 v131, 0
	v_mov_b32_e32 v132, 0
	v_mov_b32_e32 v133, 0
	v_mov_b32_e32 v134, 0
	v_mov_b32_e32 v135, 0
	v_mov_b32_e32 v144, 0
	v_mov_b32_e32 v145, 0
	v_mov_b32_e32 v146, 0
	v_mov_b32_e32 v147, 0
	v_mov_b32_e32 v148, 0
	v_mov_b32_e32 v149, 0
	v_mov_b32_e32 v150, 0
	v_mov_b32_e32 v151, 0
	global_load_dwordx4 v[0:3], v[152:153], off
	global_load_dwordx4 v[4:7], v[154:155], off
	global_load_dwordx4 v[8:11], v[156:157], off
	global_load_dwordx4 v[12:15], v[158:159], off
	global_load_dwordx4 v[16:19], v[152:153], off offset:64
	global_load_dwordx4 v[20:23], v[154:155], off offset:64
	global_load_dwordx4 v[24:27], v[156:157], off offset:64
	global_load_dwordx4 v[28:31], v[158:159], off offset:64
	s_waitcnt vmcnt(0)
	v_mfma_f32_16x16x32_bf16 v[128:131], v[0:3], v[8:11], v[128:131]
	v_mfma_f32_16x16x32_bf16 v[132:135], v[4:7], v[8:11], v[132:135]
	v_mfma_f32_16x16x32_bf16 v[144:147], v[0:3], v[12:15], v[144:147]
	v_mfma_f32_16x16x32_bf16 v[148:151], v[4:7], v[12:15], v[148:151]
	v_mfma_f32_16x16x32_bf16 v[128:131], v[16:19], v[24:27], v[128:131]
	v_mfma_f32_16x16x32_bf16 v[132:135], v[20:23], v[24:27], v[132:135]
	v_mfma_f32_16x16x32_bf16 v[144:147], v[16:19], v[28:31], v[144:147]
	v_mfma_f32_16x16x32_bf16 v[148:151], v[20:23], v[28:31], v[148:151]
	s_nop 7
	s_nop 7
	v_lshlrev_b32_e32 v170, 12, v162
	v_lshl_add_u32 v170, v136, 4, v170
	ds_write_b128 v170, v[128:131]
	ds_write_b128 v170, v[132:135] offset:1024
	ds_write_b128 v170, v[144:147] offset:2048
	ds_write_b128 v170, v[148:151] offset:3072
	s_waitcnt lgkmcnt(0)
	s_barrier
	s_cmp_ge_u32 s80, 4
	s_cbranch_scc1 .Lmgf_end
	s_lshl_b32 s84, s80, 10
	v_lshlrev_b32_e32 v171, 4, v136
	v_add_u32_e32 v171, s84, v171
	ds_read_b128 v[0:3], v171
	ds_read_b128 v[4:7], v171 offset:4096
	ds_read_b128 v[8:11], v171 offset:8192
	ds_read_b128 v[12:15], v171 offset:12288
	ds_read_b128 v[16:19], v171 offset:16384
	ds_read_b128 v[20:23], v171 offset:20480
	ds_read_b128 v[24:27], v171 offset:24576
	ds_read_b128 v[28:31], v171 offset:28672
	s_lshr_b32 s84, s80, 1
	s_lshl_b32 s84, s84, 4
	s_lshl_b32 s85, s81, 5
	s_add_i32 s84, s84, s85
	s_addk_i32 s84, 0x4000
	s_and_b32 s85, s80, 1
	s_lshl_b32 s85, s85, 4
	s_lshl_b32 s83, s82, 5
	s_add_i32 s85, s85, s83
	v_add_u32_e32 v165, s84, v160
	v_lshl_add_u32 v164, v161, 2, s85
	v_lshlrev_b32_e32 v166, 12, v165
	v_lshl_add_u32 v166, v164, 2, v166
	v_mov_b32_e32 v167, 0
	s_add_u32 s86, s74, 0x5000000
	s_addc_u32 s87, s75, 0
	v_lshl_add_u64 v[168:169], s[86:87], 0, v[166:167]
	global_load_dwordx4 v[32:35], v[168:169], off
	v_lshrrev_b32_e32 v172, 1, v166
	v_mov_b32_e32 v173, 0
	s_add_u32 s86, s74, 0x9100000
	s_addc_u32 s87, s75, 0
	v_lshl_add_u64 v[172:173], s[86:87], 0, v[172:173]
	v_lshlrev_b32_e32 v166, 2, v165
	s_add_u32 s86, s74, 0x12bb1400
	s_addc_u32 s87, s75, 0
	v_lshl_add_u64 v[166:167], s[86:87], 0, v[166:167]
	s_waitcnt lgkmcnt(0)
	v_add_f32_e32 v0, v0, v4
	v_add_f32_e32 v1, v1, v5
	v_add_f32_e32 v2, v2, v6
	v_add_f32_e32 v3, v3, v7
	v_add_f32_e32 v0, v0, v8
	v_add_f32_e32 v1, v1, v9
	v_add_f32_e32 v2, v2, v10
	v_add_f32_e32 v3, v3, v11
	v_add_f32_e32 v0, v0, v12
	v_add_f32_e32 v1, v1, v13
	v_add_f32_e32 v2, v2, v14
	v_add_f32_e32 v3, v3, v15
	v_add_f32_e32 v0, v0, v16
	v_add_f32_e32 v1, v1, v17
	v_add_f32_e32 v2, v2, v18
	v_add_f32_e32 v3, v3, v19
	v_add_f32_e32 v0, v0, v20
	v_add_f32_e32 v1, v1, v21
	v_add_f32_e32 v2, v2, v22
	v_add_f32_e32 v3, v3, v23
	v_add_f32_e32 v0, v0, v24
	v_add_f32_e32 v1, v1, v25
	v_add_f32_e32 v2, v2, v26
	v_add_f32_e32 v3, v3, v27
	v_add_f32_e32 v0, v0, v28
	v_add_f32_e32 v1, v1, v29
	v_add_f32_e32 v2, v2, v30
	v_add_f32_e32 v3, v3, v31
	s_waitcnt vmcnt(0)
	v_fma_f32 v32, v0, 1.0, v32
	v_fma_f32 v33, v1, 1.0, v33
	v_fma_f32 v34, v2, 1.0, v34
	v_fma_f32 v35, v3, 1.0, v35
	global_store_dwordx4 v[168:169], v[32:35], off
	v_cvt_pk_bf16_f32 v36, v32, v33
	v_cvt_pk_bf16_f32 v37, v34, v35
	global_store_dwordx2 v[172:173], v[36:37], off
	v_mul_f32_e32 v38, v32, v32
	v_fmac_f32_e32 v38, v33, v33
	v_fmac_f32_e32 v38, v34, v34
	v_fmac_f32_e32 v38, v35, v35
	v_xor_b32_e32 v39, 16, v136
	v_lshlrev_b32_e32 v39, 2, v39
	ds_bpermute_b32 v40, v39, v38
	v_xor_b32_e32 v41, 32, v136
	v_lshlrev_b32_e32 v41, 2, v41
	s_waitcnt lgkmcnt(0)
	v_add_f32_e32 v38, v38, v40
	ds_bpermute_b32 v40, v41, v38
	s_waitcnt lgkmcnt(0)
	v_add_f32_e32 v38, v38, v40
	v_cmp_gt_u32_e64 s[82:83], 16, v136
	s_nop 1
	s_and_saveexec_b64 s[84:85], s[82:83]
	global_atomic_add_f32 v[166:167], v38, off
	s_mov_b64 exec, s[84:85]
.Lmgf_end:
	s_cmp_lt_u32 s33, 32
	s_cbranch_scc1 .Lcpyf_end
	v_lshrrev_b32_e32 v21, 6, v174
	v_and_b32_e32 v22, 63, v174
	v_lshlrev_b32_e32 v22, 4, v22
	v_readfirstlane_b32 s80, v21
	v_add_u32_e32 v23, 0x1000, v22
	v_readfirstlane_b32 s92, v235
	v_readfirstlane_b32 s93, v236
	v_readfirstlane_b32 s94, v237
	v_readfirstlane_b32 s95, v238
	v_readfirstlane_b32 s98, v239
	v_readfirstlane_b32 s99, v240
	s_add_i32 s80, s80, s33
	s_add_i32 s80, s80, 0x122a8
	s_sub_i32 s100, s78, 4
	s_lshl_b32 s100, s100, 3
.Lcpyf_loop:
	s_add_i32 s101, s80, s100
	s_cmp_lt_u32 s101, 0x13650
	s_cbranch_scc0 .Lcpyf_tail
	s_mul_hi_u32 s81, s80, 0x2ad5802b
	s_lshr_b32 s81, s81, 8
	s_mul_i32 s82, s81, 0x5fa
	s_sub_i32 s82, s80, s82
	s_lshl_b32 s82, s82, 13
	s_and_b32 s83, s81, 31
	s_mul_i32 s83, s83, 0xc00000
	s_add_i32 s82, s82, s83
	s_cmp_lt_u32 s81, 32
	s_cselect_b32 s84, s92, s94
	s_cselect_b32 s85, s93, s95
	s_mov_b32 s83, 0x1f210000
	s_cselect_b32 s83, 0x7210000, s83
	s_add_u32 s84, s84, s82
	s_addc_u32 s85, s85, 0
	s_add_u32 s84, s84, 0xc000
	s_addc_u32 s85, s85, 0
	s_add_u32 s83, s83, s82
	s_add_u32 s86, s98, s83
	s_addc_u32 s87, s99, 0
	s_mul_hi_u32 s81, s101, 0x2ad5802b
	s_lshr_b32 s81, s81, 8
	s_mul_i32 s82, s81, 0x5fa
	s_sub_i32 s82, s101, s82
	s_lshl_b32 s82, s82, 13
	s_and_b32 s83, s81, 31
	s_mul_i32 s83, s83, 0xc00000
	s_add_i32 s82, s82, s83
	s_cmp_lt_u32 s81, 32
	s_cselect_b32 s88, s92, s94
	s_cselect_b32 s89, s93, s95
	s_mov_b32 s83, 0x1f210000
	s_cselect_b32 s83, 0x7210000, s83
	s_add_u32 s88, s88, s82
	s_addc_u32 s89, s89, 0
	s_add_u32 s88, s88, 0xc000
	s_addc_u32 s89, s89, 0
	s_add_u32 s83, s83, s82
	s_add_u32 s90, s98, s83
	s_addc_u32 s91, s99, 0
	global_load_dwordx4 v[64:67], v22, s[84:85] nt
	global_load_dwordx4 v[68:71], v22, s[84:85] offset:1024 nt
	global_load_dwordx4 v[72:75], v22, s[84:85] offset:2048 nt
	global_load_dwordx4 v[76:79], v22, s[84:85] offset:3072 nt
	global_load_dwordx4 v[80:83], v23, s[84:85] nt
	global_load_dwordx4 v[84:87], v23, s[84:85] offset:1024 nt
	global_load_dwordx4 v[88:91], v23, s[84:85] offset:2048 nt
	global_load_dwordx4 v[92:95], v23, s[84:85] offset:3072 nt
	global_load_dwordx4 v[96:99], v22, s[88:89] nt
	global_load_dwordx4 v[100:103], v22, s[88:89] offset:1024 nt
	global_load_dwordx4 v[104:107], v22, s[88:89] offset:2048 nt
	global_load_dwordx4 v[108:111], v22, s[88:89] offset:3072 nt
	global_load_dwordx4 v[112:115], v23, s[88:89] nt
	global_load_dwordx4 v[116:119], v23, s[88:89] offset:1024 nt
	global_load_dwordx4 v[120:123], v23, s[88:89] offset:2048 nt
	global_load_dwordx4 v[124:127], v23, s[88:89] offset:3072 nt
	s_waitcnt vmcnt(15)
	global_store_dwordx4 v22, v[64:67], s[86:87] nt
	s_waitcnt vmcnt(15)
	global_store_dwordx4 v22, v[68:71], s[86:87] offset:1024 nt
	s_waitcnt vmcnt(15)
	global_store_dwordx4 v22, v[72:75], s[86:87] offset:2048 nt
	s_waitcnt vmcnt(15)
	global_store_dwordx4 v22, v[76:79], s[86:87] offset:3072 nt
	s_waitcnt vmcnt(15)
	global_store_dwordx4 v23, v[80:83], s[86:87] nt
	s_waitcnt vmcnt(15)
	global_store_dwordx4 v23, v[84:87], s[86:87] offset:1024 nt
	s_waitcnt vmcnt(15)
	global_store_dwordx4 v23, v[88:91], s[86:87] offset:2048 nt
	s_waitcnt vmcnt(15)
	global_store_dwordx4 v23, v[92:95], s[86:87] offset:3072 nt
	s_waitcnt vmcnt(15)
	global_store_dwordx4 v22, v[96:99], s[90:91] nt
	s_waitcnt vmcnt(15)
	global_store_dwordx4 v22, v[100:103], s[90:91] offset:1024 nt
	s_waitcnt vmcnt(15)
	global_store_dwordx4 v22, v[104:107], s[90:91] offset:2048 nt
	s_waitcnt vmcnt(15)
	global_store_dwordx4 v22, v[108:111], s[90:91] offset:3072 nt
	s_waitcnt vmcnt(15)
	global_store_dwordx4 v23, v[112:115], s[90:91] nt
	s_waitcnt vmcnt(15)
	global_store_dwordx4 v23, v[116:119], s[90:91] offset:1024 nt
	s_waitcnt vmcnt(15)
	global_store_dwordx4 v23, v[120:123], s[90:91] offset:2048 nt
	s_waitcnt vmcnt(15)
	global_store_dwordx4 v23, v[124:127], s[90:91] offset:3072 nt
	s_add_i32 s80, s101, s100
	s_branch .Lcpyf_loop
.Lcpyf_tail:
	s_cmp_lt_u32 s80, 0x13650
	s_cbranch_scc0 .Lcpyf_end
	s_mul_hi_u32 s81, s80, 0x2ad5802b
	s_lshr_b32 s81, s81, 8
	s_mul_i32 s82, s81, 0x5fa
	s_sub_i32 s82, s80, s82
	s_lshl_b32 s82, s82, 13
	s_and_b32 s83, s81, 31
	s_mul_i32 s83, s83, 0xc00000
	s_add_i32 s82, s82, s83
	s_cmp_lt_u32 s81, 32
	s_cselect_b32 s84, s92, s94
	s_cselect_b32 s85, s93, s95
	s_mov_b32 s83, 0x1f210000
	s_cselect_b32 s83, 0x7210000, s83
	s_add_u32 s84, s84, s82
	s_addc_u32 s85, s85, 0
	s_add_u32 s84, s84, 0xc000
	s_addc_u32 s85, s85, 0
	s_add_u32 s83, s83, s82
	s_add_u32 s86, s98, s83
	s_addc_u32 s87, s99, 0
	global_load_dwordx4 v[64:67], v22, s[84:85] nt
	global_load_dwordx4 v[68:71], v22, s[84:85] offset:1024 nt
	global_load_dwordx4 v[72:75], v22, s[84:85] offset:2048 nt
	global_load_dwordx4 v[76:79], v22, s[84:85] offset:3072 nt
	global_load_dwordx4 v[80:83], v23, s[84:85] nt
	global_load_dwordx4 v[84:87], v23, s[84:85] offset:1024 nt
	global_load_dwordx4 v[88:91], v23, s[84:85] offset:2048 nt
	global_load_dwordx4 v[92:95], v23, s[84:85] offset:3072 nt
	s_waitcnt vmcnt(7)
	global_store_dwordx4 v22, v[64:67], s[86:87] nt
	s_waitcnt vmcnt(7)
	global_store_dwordx4 v22, v[68:71], s[86:87] offset:1024 nt
	s_waitcnt vmcnt(7)
	global_store_dwordx4 v22, v[72:75], s[86:87] offset:2048 nt
	s_waitcnt vmcnt(7)
	global_store_dwordx4 v22, v[76:79], s[86:87] offset:3072 nt
	s_waitcnt vmcnt(7)
	global_store_dwordx4 v23, v[80:83], s[86:87] nt
	s_waitcnt vmcnt(7)
	global_store_dwordx4 v23, v[84:87], s[86:87] offset:1024 nt
	s_waitcnt vmcnt(7)
	global_store_dwordx4 v23, v[88:91], s[86:87] offset:2048 nt
	s_waitcnt vmcnt(7)
	global_store_dwordx4 v23, v[92:95], s[86:87] offset:3072 nt

.LBB0_1461:
	s_cmp_lt_u32 s33, 1200
	s_cbranch_scc1 .Lcpyg_end
	v_lshrrev_b32_e32 v21, 6, v174
	v_and_b32_e32 v22, 63, v174
	v_lshlrev_b32_e32 v22, 4, v22
	v_readfirstlane_b32 s80, v21
	v_add_u32_e32 v23, 0x1000, v22
	v_readfirstlane_b32 s92, v235
	v_readfirstlane_b32 s93, v236
	v_readfirstlane_b32 s94, v237
	v_readfirstlane_b32 s95, v238
	v_readfirstlane_b32 s98, v239
	v_readfirstlane_b32 s99, v240
	s_add_i32 s80, s80, s33
	s_add_i32 s80, s80, 0x131a0
	s_sub_i32 s100, s78, 150
	s_lshl_b32 s100, s100, 3
.Lcpyg_loop:
	s_add_i32 s101, s80, s100
	s_cmp_lt_u32 s101, 0x15590
	s_cbranch_scc0 .Lcpyg_tail
	s_mul_hi_u32 s81, s80, 0x2ad5802b
	s_lshr_b32 s81, s81, 8
	s_mul_i32 s82, s81, 0x5fa
	s_sub_i32 s82, s80, s82
	s_lshl_b32 s82, s82, 13
	s_and_b32 s83, s81, 31
	s_mul_i32 s83, s83, 0xc00000
	s_add_i32 s82, s82, s83
	s_cmp_lt_u32 s81, 32
	s_cselect_b32 s84, s92, s94
	s_cselect_b32 s85, s93, s95
	s_mov_b32 s83, 0x1f210000
	s_cselect_b32 s83, 0x7210000, s83
	s_add_u32 s84, s84, s82
	s_addc_u32 s85, s85, 0
	s_add_u32 s84, s84, 0xc000
	s_addc_u32 s85, s85, 0
	s_add_u32 s83, s83, s82
	s_add_u32 s86, s98, s83
	s_addc_u32 s87, s99, 0
	s_mul_hi_u32 s81, s101, 0x2ad5802b
	s_lshr_b32 s81, s81, 8
	s_mul_i32 s82, s81, 0x5fa
	s_sub_i32 s82, s101, s82
	s_lshl_b32 s82, s82, 13
	s_and_b32 s83, s81, 31
	s_mul_i32 s83, s83, 0xc00000
	s_add_i32 s82, s82, s83
	s_cmp_lt_u32 s81, 32
	s_cselect_b32 s88, s92, s94
	s_cselect_b32 s89, s93, s95
	s_mov_b32 s83, 0x1f210000
	s_cselect_b32 s83, 0x7210000, s83
	s_add_u32 s88, s88, s82
	s_addc_u32 s89, s89, 0
	s_add_u32 s88, s88, 0xc000
	s_addc_u32 s89, s89, 0
	s_add_u32 s83, s83, s82
	s_add_u32 s90, s98, s83
	s_addc_u32 s91, s99, 0
	global_load_dwordx4 v[64:67], v22, s[84:85] nt
	global_load_dwordx4 v[68:71], v22, s[84:85] offset:1024 nt
	global_load_dwordx4 v[72:75], v22, s[84:85] offset:2048 nt
	global_load_dwordx4 v[76:79], v22, s[84:85] offset:3072 nt
	global_load_dwordx4 v[80:83], v23, s[84:85] nt
	global_load_dwordx4 v[84:87], v23, s[84:85] offset:1024 nt
	global_load_dwordx4 v[88:91], v23, s[84:85] offset:2048 nt
	global_load_dwordx4 v[92:95], v23, s[84:85] offset:3072 nt
	global_load_dwordx4 v[96:99], v22, s[88:89] nt
	global_load_dwordx4 v[100:103], v22, s[88:89] offset:1024 nt
	global_load_dwordx4 v[104:107], v22, s[88:89] offset:2048 nt
	global_load_dwordx4 v[108:111], v22, s[88:89] offset:3072 nt
	global_load_dwordx4 v[112:115], v23, s[88:89] nt
	global_load_dwordx4 v[116:119], v23, s[88:89] offset:1024 nt
	global_load_dwordx4 v[120:123], v23, s[88:89] offset:2048 nt
	global_load_dwordx4 v[124:127], v23, s[88:89] offset:3072 nt
	s_waitcnt vmcnt(15)
	global_store_dwordx4 v22, v[64:67], s[86:87] nt
	s_waitcnt vmcnt(15)
	global_store_dwordx4 v22, v[68:71], s[86:87] offset:1024 nt
	s_waitcnt vmcnt(15)
	global_store_dwordx4 v22, v[72:75], s[86:87] offset:2048 nt
	s_waitcnt vmcnt(15)
	global_store_dwordx4 v22, v[76:79], s[86:87] offset:3072 nt
	s_waitcnt vmcnt(15)
	global_store_dwordx4 v23, v[80:83], s[86:87] nt
	s_waitcnt vmcnt(15)
	global_store_dwordx4 v23, v[84:87], s[86:87] offset:1024 nt
	s_waitcnt vmcnt(15)
	global_store_dwordx4 v23, v[88:91], s[86:87] offset:2048 nt
	s_waitcnt vmcnt(15)
	global_store_dwordx4 v23, v[92:95], s[86:87] offset:3072 nt
	s_waitcnt vmcnt(15)
	global_store_dwordx4 v22, v[96:99], s[90:91] nt
	s_waitcnt vmcnt(15)
	global_store_dwordx4 v22, v[100:103], s[90:91] offset:1024 nt
	s_waitcnt vmcnt(15)
	global_store_dwordx4 v22, v[104:107], s[90:91] offset:2048 nt
	s_waitcnt vmcnt(15)
	global_store_dwordx4 v22, v[108:111], s[90:91] offset:3072 nt
	s_waitcnt vmcnt(15)
	global_store_dwordx4 v23, v[112:115], s[90:91] nt
	s_waitcnt vmcnt(15)
	global_store_dwordx4 v23, v[116:119], s[90:91] offset:1024 nt
	s_waitcnt vmcnt(15)
	global_store_dwordx4 v23, v[120:123], s[90:91] offset:2048 nt
	s_waitcnt vmcnt(15)
	global_store_dwordx4 v23, v[124:127], s[90:91] offset:3072 nt
	s_add_i32 s80, s101, s100
	s_branch .Lcpyg_loop
.Lcpyg_tail:
	s_cmp_lt_u32 s80, 0x15590
	s_cbranch_scc0 .Lcpyg_end
	s_mul_hi_u32 s81, s80, 0x2ad5802b
	s_lshr_b32 s81, s81, 8
	s_mul_i32 s82, s81, 0x5fa
	s_sub_i32 s82, s80, s82
	s_lshl_b32 s82, s82, 13
	s_and_b32 s83, s81, 31
	s_mul_i32 s83, s83, 0xc00000
	s_add_i32 s82, s82, s83
	s_cmp_lt_u32 s81, 32
	s_cselect_b32 s84, s92, s94
	s_cselect_b32 s85, s93, s95
	s_mov_b32 s83, 0x1f210000
	s_cselect_b32 s83, 0x7210000, s83
	s_add_u32 s84, s84, s82
	s_addc_u32 s85, s85, 0
	s_add_u32 s84, s84, 0xc000
	s_addc_u32 s85, s85, 0
	s_add_u32 s83, s83, s82
	s_add_u32 s86, s98, s83
	s_addc_u32 s87, s99, 0
	global_load_dwordx4 v[64:67], v22, s[84:85] nt
	global_load_dwordx4 v[68:71], v22, s[84:85] offset:1024 nt
	global_load_dwordx4 v[72:75], v22, s[84:85] offset:2048 nt
	global_load_dwordx4 v[76:79], v22, s[84:85] offset:3072 nt
	global_load_dwordx4 v[80:83], v23, s[84:85] nt
	global_load_dwordx4 v[84:87], v23, s[84:85] offset:1024 nt
	global_load_dwordx4 v[88:91], v23, s[84:85] offset:2048 nt
	global_load_dwordx4 v[92:95], v23, s[84:85] offset:3072 nt
	s_waitcnt vmcnt(7)
	global_store_dwordx4 v22, v[64:67], s[86:87] nt
	s_waitcnt vmcnt(7)
	global_store_dwordx4 v22, v[68:71], s[86:87] offset:1024 nt
	s_waitcnt vmcnt(7)
	global_store_dwordx4 v22, v[72:75], s[86:87] offset:2048 nt
	s_waitcnt vmcnt(7)
	global_store_dwordx4 v22, v[76:79], s[86:87] offset:3072 nt
	s_waitcnt vmcnt(7)
	global_store_dwordx4 v23, v[80:83], s[86:87] nt
	s_waitcnt vmcnt(7)
	global_store_dwordx4 v23, v[84:87], s[86:87] offset:1024 nt
	s_waitcnt vmcnt(7)
	global_store_dwordx4 v23, v[88:91], s[86:87] offset:2048 nt
	s_waitcnt vmcnt(7)
	global_store_dwordx4 v23, v[92:95], s[86:87] offset:3072 nt

.LBB0_1481:
	s_or_b64 exec, exec, s[6:7]
	v_readlane_b32 s4, v234, 2
	v_mov_b32_e32 v8, v174
	v_readlane_b32 s5, v234, 3
	s_barrier
	s_and_b64 vcc, exec, s[4:5]
	v_readfirstlane_b32 s3, v8
	s_cbranch_vccnz .LBB0_1487
	s_ashr_i32 s4, s2, 31
	s_lshr_b32 s4, s4, 29
	s_add_i32 s5, s2, s4
	s_and_b32 s4, s5, -8
	s_sub_i32 s4, s2, s4
	s_cmp_gt_i32 s4, -1
	s_cbranch_scc0 .LBB0_1484
	s_lshl_b32 s6, s4, 5
	s_or_b32 s8, s6, 0
	s_ashr_i32 s5, s5, 3
	s_cbranch_execz .LBB0_1485
	s_branch .LBB0_1486

.LBB0_1490:
	s_add_u32 s12, s74, 0x12bc1800
	s_addc_u32 s13, s75, 0
	s_lshl_b32 s5, s5, 5
	s_mov_b64 s[14:15], 0x80
	s_and_b32 s10, s5, 0x60
	s_add_i32 m0, s29, 0x18000
	v_lshl_add_u64 v[6:7], v[6:7], 0, s[14:15]
	s_lshl_b32 s7, s4, 13
	s_lshl_b32 s5, s10, 7
	s_waitcnt vmcnt(4)
	s_barrier
	global_load_lds_dwordx4 v[6:7], off
	v_lshl_add_u64 v[4:5], v[4:5], 0, s[14:15]
	s_add_i32 m0, s29, 0x1a000
	s_add_i32 s36, s29, 0x8000
	s_add_i32 s37, s29, 0xa000
	global_load_lds_dwordx4 v[4:5], off
	v_lshl_add_u64 v[2:3], v[2:3], 0, s[14:15]
	s_mov_b32 m0, s36
	s_add_u32 s8, s20, 0xb0080
	global_load_lds_dwordx4 v[2:3], off
	v_lshl_add_u64 v[0:1], v[0:1], 0, s[14:15]
	s_mov_b32 m0, s37
	s_addc_u32 s9, s21, 0
	global_load_lds_dwordx4 v[0:1], off
	s_add_i32 m0, s29, 0x1c000
	v_lshl_add_u64 v[0:1], s[8:9], 0, v[130:131]
	global_load_lds_dwordx4 v[0:1], off
	v_lshl_add_u64 v[0:1], s[8:9], 0, v[134:135]
	s_add_i32 m0, s29, 0x1e000
	s_mov_b64 s[8:9], 0xb0080
	global_load_lds_dwordx4 v[0:1], off
	v_bfe_u32 v0, v8, 4, 2
	v_and_b32_e32 v1, 15, v8
	v_lshlrev_b32_e32 v2, 4, v0
	v_lshl_or_b32 v148, s4, 6, v1
	v_lshl_or_b32 v1, v1, 6, v2
	v_lshlrev_b32_e32 v2, 2, v8
	v_and_b32_e32 v2, 32, v2
	v_bitop3_b32 v3, v1, s7, v2 bitop3:0xde
	v_bitop3_b32 v149, v1, s5, v2 bitop3:0xde
	v_cmp_eq_u32_e64 s[4:5], 0, v0
	v_lshl_or_b32 v150, v0, 3, s10
	v_lshrrev_b32_e32 v1, 1, v9
	v_mul_lo_u32 v0, v11, s6
	s_mov_b32 s7, 0xb000
	v_mad_u64_u32 v[0:1], s[10:11], v1, s7, v[0:1]
	v_or_b32_e32 v0, v0, v10
	v_add_lshl_u32 v0, v0, v12, 1
	v_mov_b32_e32 v1, v131
	v_lshl_add_u64 v[136:137], v[0:1], 0, s[8:9]
	v_lshrrev_b32_e32 v1, 1, v13
	v_mul_lo_u32 v0, v14, s6
	v_mad_u64_u32 v[0:1], s[6:7], v1, s7, v[0:1]
	s_waitcnt vmcnt(6)
	v_or_b32_e32 v0, v0, v15
	v_add_lshl_u32 v0, v0, v16, 1
	v_mov_b32_e32 v1, v131
	s_add_i32 s43, 0, 0x10000
	s_add_i32 s46, 0, 0x14000
	s_bfe_i64 s[16:17], s[78:79], 0x200000
	s_ashr_i32 s42, s2, 31
	v_lshl_add_u64 v[138:139], v[0:1], 0, s[8:9]
	v_mov_b64_e32 v[140:141], 0x100
	v_mov_b64_e32 v[142:143], 0xff
	v_add_u32_e32 v151, s43, v149
	v_add_u32_e32 v152, 0, v3
	v_add_u32_e32 v153, s46, v149
	v_mbcnt_hi_u32_b32 v154, -1, v175
	s_barrier
	s_branch .LBB0_1492

.LBB0_1523:
	v_and_b32_e32 v160, 15, v174
	v_bfe_u32 v161, v174, 4, 2
	v_lshrrev_b32_e32 v162, 6, v174
	v_and_b32_e32 v136, 63, v174
	v_readfirstlane_b32 s80, v162
	s_lshr_b32 s81, s33, 8
	s_lshr_b32 s82, s33, 3
	s_and_b32 s82, s82, 31
	s_mul_i32 s83, s80, 704
	v_lshlrev_b32_e32 v164, 4, v161
	v_mov_b32_e32 v167, 0
	s_lshl_b32 s84, s82, 5
	v_add_u32_e32 v165, s84, v160
	v_mul_u32_u24_e32 v166, 0x1600, v165
	v_add3_u32 v166, v166, v164, s83
	s_add_u32 s86, s74, 0x3c80000
	s_addc_u32 s87, s75, 0
	s_mov_b32 s88, 0x16000
	s_mov_b32 s89, 0
	v_lshl_add_u64 v[152:153], s[86:87], 0, v[166:167]
	v_lshl_add_u64 v[154:155], v[152:153], 0, s[88:89]
	s_lshl_b32 s84, s81, 5
	v_add_u32_e32 v165, s84, v160
	v_mul_u32_u24_e32 v166, 0x1600, v165
	v_add3_u32 v166, v166, v164, s83
	s_add_u32 s90, s74, 0x10980000
	s_addc_u32 s91, s75, 0
	v_lshl_add_u64 v[156:157], s[90:91], 0, v[166:167]
	v_lshl_add_u64 v[158:159], v[156:157], 0, s[88:89]
	v_mov_b32_e32 v128, 0
	v_mov_b32_e32 v129, 0
	v_mov_b32_e32 v130, 0
	v_mov_b32_e32 v131, 0
	v_mov_b32_e32 v132, 0
	v_mov_b32_e32 v133, 0
	v_mov_b32_e32 v134, 0
	v_mov_b32_e32 v135, 0
	v_mov_b32_e32 v144, 0
	v_mov_b32_e32 v145, 0
	v_mov_b32_e32 v146, 0
	v_mov_b32_e32 v147, 0
	v_mov_b32_e32 v148, 0
	v_mov_b32_e32 v149, 0
	v_mov_b32_e32 v150, 0
	v_mov_b32_e32 v151, 0
	global_load_dwordx4 v[0:3], v[152:153], off
	global_load_dwordx4 v[4:7], v[154:155], off
	global_load_dwordx4 v[8:11], v[156:157], off
	global_load_dwordx4 v[12:15], v[158:159], off
	global_load_dwordx4 v[16:19], v[152:153], off offset:64
	global_load_dwordx4 v[20:23], v[154:155], off offset:64
	global_load_dwordx4 v[24:27], v[156:157], off offset:64
	global_load_dwordx4 v[28:31], v[158:159], off offset:64
	global_load_dwordx4 v[32:35], v[152:153], off offset:128
	global_load_dwordx4 v[36:39], v[154:155], off offset:128
	global_load_dwordx4 v[40:43], v[156:157], off offset:128
	global_load_dwordx4 v[44:47], v[158:159], off offset:128
	global_load_dwordx4 v[48:51], v[152:153], off offset:192
	global_load_dwordx4 v[52:55], v[154:155], off offset:192
	global_load_dwordx4 v[56:59], v[156:157], off offset:192
	global_load_dwordx4 v[60:63], v[158:159], off offset:192
	global_load_dwordx4 v[64:67], v[152:153], off offset:256
	global_load_dwordx4 v[68:71], v[154:155], off offset:256
	global_load_dwordx4 v[72:75], v[156:157], off offset:256
	global_load_dwordx4 v[76:79], v[158:159], off offset:256
	global_load_dwordx4 v[80:83], v[152:153], off offset:320
	global_load_dwordx4 v[84:87], v[154:155], off offset:320
	global_load_dwordx4 v[88:91], v[156:157], off offset:320
	global_load_dwordx4 v[92:95], v[158:159], off offset:320
	global_load_dwordx4 v[96:99], v[152:153], off offset:384
	global_load_dwordx4 v[100:103], v[154:155], off offset:384
	global_load_dwordx4 v[104:107], v[156:157], off offset:384
	global_load_dwordx4 v[108:111], v[158:159], off offset:384
	global_load_dwordx4 v[112:115], v[152:153], off offset:448
	global_load_dwordx4 v[116:119], v[154:155], off offset:448
	global_load_dwordx4 v[120:123], v[156:157], off offset:448
	global_load_dwordx4 v[124:127], v[158:159], off offset:448
	s_waitcnt vmcnt(16)
	v_mfma_f32_16x16x32_bf16 v[128:131], v[0:3], v[8:11], v[128:131]
	v_mfma_f32_16x16x32_bf16 v[132:135], v[4:7], v[8:11], v[132:135]
	v_mfma_f32_16x16x32_bf16 v[144:147], v[0:3], v[12:15], v[144:147]
	v_mfma_f32_16x16x32_bf16 v[148:151], v[4:7], v[12:15], v[148:151]
	v_mfma_f32_16x16x32_bf16 v[128:131], v[16:19], v[24:27], v[128:131]
	v_mfma_f32_16x16x32_bf16 v[132:135], v[20:23], v[24:27], v[132:135]
	v_mfma_f32_16x16x32_bf16 v[144:147], v[16:19], v[28:31], v[144:147]
	v_mfma_f32_16x16x32_bf16 v[148:151], v[20:23], v[28:31], v[148:151]
	v_mfma_f32_16x16x32_bf16 v[128:131], v[32:35], v[40:43], v[128:131]
	v_mfma_f32_16x16x32_bf16 v[132:135], v[36:39], v[40:43], v[132:135]
	v_mfma_f32_16x16x32_bf16 v[144:147], v[32:35], v[44:47], v[144:147]
	v_mfma_f32_16x16x32_bf16 v[148:151], v[36:39], v[44:47], v[148:151]
	v_mfma_f32_16x16x32_bf16 v[128:131], v[48:51], v[56:59], v[128:131]
	v_mfma_f32_16x16x32_bf16 v[132:135], v[52:55], v[56:59], v[132:135]
	v_mfma_f32_16x16x32_bf16 v[144:147], v[48:51], v[60:63], v[144:147]
	v_mfma_f32_16x16x32_bf16 v[148:151], v[52:55], v[60:63], v[148:151]
	global_load_dwordx4 v[0:3], v[152:153], off offset:512
	global_load_dwordx4 v[4:7], v[154:155], off offset:512
	global_load_dwordx4 v[8:11], v[156:157], off offset:512
	global_load_dwordx4 v[12:15], v[158:159], off offset:512
	global_load_dwordx4 v[16:19], v[152:153], off offset:576
	global_load_dwordx4 v[20:23], v[154:155], off offset:576
	global_load_dwordx4 v[24:27], v[156:157], off offset:576
	global_load_dwordx4 v[28:31], v[158:159], off offset:576
	global_load_dwordx4 v[32:35], v[152:153], off offset:640
	global_load_dwordx4 v[36:39], v[154:155], off offset:640
	global_load_dwordx4 v[40:43], v[156:157], off offset:640
	global_load_dwordx4 v[44:47], v[158:159], off offset:640
	s_waitcnt vmcnt(12)
	v_mfma_f32_16x16x32_bf16 v[128:131], v[64:67], v[72:75], v[128:131]
	v_mfma_f32_16x16x32_bf16 v[132:135], v[68:71], v[72:75], v[132:135]
	v_mfma_f32_16x16x32_bf16 v[144:147], v[64:67], v[76:79], v[144:147]
	v_mfma_f32_16x16x32_bf16 v[148:151], v[68:71], v[76:79], v[148:151]
	v_mfma_f32_16x16x32_bf16 v[128:131], v[80:83], v[88:91], v[128:131]
	v_mfma_f32_16x16x32_bf16 v[132:135], v[84:87], v[88:91], v[132:135]
	v_mfma_f32_16x16x32_bf16 v[144:147], v[80:83], v[92:95], v[144:147]
	v_mfma_f32_16x16x32_bf16 v[148:151], v[84:87], v[92:95], v[148:151]
	v_mfma_f32_16x16x32_bf16 v[128:131], v[96:99], v[104:107], v[128:131]
	v_mfma_f32_16x16x32_bf16 v[132:135], v[100:103], v[104:107], v[132:135]
	v_mfma_f32_16x16x32_bf16 v[144:147], v[96:99], v[108:111], v[144:147]
	v_mfma_f32_16x16x32_bf16 v[148:151], v[100:103], v[108:111], v[148:151]
	v_mfma_f32_16x16x32_bf16 v[128:131], v[112:115], v[120:123], v[128:131]
	v_mfma_f32_16x16x32_bf16 v[132:135], v[116:119], v[120:123], v[132:135]
	v_mfma_f32_16x16x32_bf16 v[144:147], v[112:115], v[124:127], v[144:147]
	v_mfma_f32_16x16x32_bf16 v[148:151], v[116:119], v[124:127], v[148:151]
	s_waitcnt vmcnt(0)
	v_mfma_f32_16x16x32_bf16 v[128:131], v[0:3], v[8:11], v[128:131]
	v_mfma_f32_16x16x32_bf16 v[132:135], v[4:7], v[8:11], v[132:135]
	v_mfma_f32_16x16x32_bf16 v[144:147], v[0:3], v[12:15], v[144:147]
	v_mfma_f32_16x16x32_bf16 v[148:151], v[4:7], v[12:15], v[148:151]
	v_mfma_f32_16x16x32_bf16 v[128:131], v[16:19], v[24:27], v[128:131]
	v_mfma_f32_16x16x32_bf16 v[132:135], v[20:23], v[24:27], v[132:135]
	v_mfma_f32_16x16x32_bf16 v[144:147], v[16:19], v[28:31], v[144:147]
	v_mfma_f32_16x16x32_bf16 v[148:151], v[20:23], v[28:31], v[148:151]
	v_mfma_f32_16x16x32_bf16 v[128:131], v[32:35], v[40:43], v[128:131]
	v_mfma_f32_16x16x32_bf16 v[132:135], v[36:39], v[40:43], v[132:135]
	v_mfma_f32_16x16x32_bf16 v[144:147], v[32:35], v[44:47], v[144:147]
	v_mfma_f32_16x16x32_bf16 v[148:151], v[36:39], v[44:47], v[148:151]
	s_nop 7
	s_nop 7
	v_lshlrev_b32_e32 v170, 12, v162
	v_lshl_add_u32 v170, v136, 4, v170
	ds_write_b128 v170, v[128:131]
	ds_write_b128 v170, v[132:135] offset:1024
	ds_write_b128 v170, v[144:147] offset:2048
	ds_write_b128 v170, v[148:151] offset:3072
	s_waitcnt lgkmcnt(0)
	s_barrier
	s_cmp_ge_u32 s80, 4
	s_cbranch_scc1 .Lmg4_end
	s_lshl_b32 s84, s80, 10
	v_lshlrev_b32_e32 v171, 4, v136
	v_add_u32_e32 v171, s84, v171
	ds_read_b128 v[0:3], v171
	ds_read_b128 v[4:7], v171 offset:4096
	ds_read_b128 v[8:11], v171 offset:8192
	ds_read_b128 v[12:15], v171 offset:12288
	ds_read_b128 v[16:19], v171 offset:16384
	ds_read_b128 v[20:23], v171 offset:20480
	ds_read_b128 v[24:27], v171 offset:24576
	ds_read_b128 v[28:31], v171 offset:28672
	s_lshr_b32 s84, s80, 1
	s_lshl_b32 s84, s84, 4
	s_lshl_b32 s85, s81, 5
	s_add_i32 s84, s84, s85
	s_addk_i32 s84, 0x4000
	s_and_b32 s85, s80, 1
	s_lshl_b32 s85, s85, 4
	s_lshl_b32 s83, s82, 5
	s_add_i32 s85, s85, s83
	v_add_u32_e32 v165, s84, v160
	v_lshl_add_u32 v164, v161, 2, s85
	v_lshlrev_b32_e32 v166, 12, v165
	v_lshl_add_u32 v166, v164, 2, v166
	v_mov_b32_e32 v167, 0
	s_add_u32 s86, s74, 0x5000000
	s_addc_u32 s87, s75, 0
	v_lshl_add_u64 v[168:169], s[86:87], 0, v[166:167]
	global_load_dwordx4 v[32:35], v[168:169], off
	v_lshrrev_b32_e32 v172, 1, v166
	v_mov_b32_e32 v173, 0
	s_add_u32 s86, s74, 0x9100000
	s_addc_u32 s87, s75, 0
	v_lshl_add_u64 v[172:173], s[86:87], 0, v[172:173]
	v_lshlrev_b32_e32 v166, 2, v165
	s_add_u32 s86, s74, 0x12bc1800
	s_addc_u32 s87, s75, 0
	v_lshl_add_u64 v[166:167], s[86:87], 0, v[166:167]
	s_waitcnt lgkmcnt(0)
	v_add_f32_e32 v0, v0, v4
	v_add_f32_e32 v1, v1, v5
	v_add_f32_e32 v2, v2, v6
	v_add_f32_e32 v3, v3, v7
	v_add_f32_e32 v0, v0, v8
	v_add_f32_e32 v1, v1, v9
	v_add_f32_e32 v2, v2, v10
	v_add_f32_e32 v3, v3, v11
	v_add_f32_e32 v0, v0, v12
	v_add_f32_e32 v1, v1, v13
	v_add_f32_e32 v2, v2, v14
	v_add_f32_e32 v3, v3, v15
	v_add_f32_e32 v0, v0, v16
	v_add_f32_e32 v1, v1, v17
	v_add_f32_e32 v2, v2, v18
	v_add_f32_e32 v3, v3, v19
	v_add_f32_e32 v0, v0, v20
	v_add_f32_e32 v1, v1, v21
	v_add_f32_e32 v2, v2, v22
	v_add_f32_e32 v3, v3, v23
	v_add_f32_e32 v0, v0, v24
	v_add_f32_e32 v1, v1, v25
	v_add_f32_e32 v2, v2, v26
	v_add_f32_e32 v3, v3, v27
	v_add_f32_e32 v0, v0, v28
	v_add_f32_e32 v1, v1, v29
	v_add_f32_e32 v2, v2, v30
	v_add_f32_e32 v3, v3, v31
	s_waitcnt vmcnt(0)
	v_fma_f32 v32, v0, 0.5, v32
	v_fma_f32 v33, v1, 0.5, v33
	v_fma_f32 v34, v2, 0.5, v34
	v_fma_f32 v35, v3, 0.5, v35
	global_store_dwordx4 v[168:169], v[32:35], off
	v_cvt_pk_bf16_f32 v36, v32, v33
	v_cvt_pk_bf16_f32 v37, v34, v35
	global_store_dwordx2 v[172:173], v[36:37], off
	v_mul_f32_e32 v38, v32, v32
	v_fmac_f32_e32 v38, v33, v33
	v_fmac_f32_e32 v38, v34, v34
	v_fmac_f32_e32 v38, v35, v35
	v_xor_b32_e32 v39, 16, v136
	v_lshlrev_b32_e32 v39, 2, v39
	ds_bpermute_b32 v40, v39, v38
	v_xor_b32_e32 v41, 32, v136
	v_lshlrev_b32_e32 v41, 2, v41
	s_waitcnt lgkmcnt(0)
	v_add_f32_e32 v38, v38, v40
	ds_bpermute_b32 v40, v41, v38
	s_waitcnt lgkmcnt(0)
	v_add_f32_e32 v38, v38, v40
	v_cmp_gt_u32_e64 s[82:83], 16, v136
	s_nop 1
	s_and_saveexec_b64 s[84:85], s[82:83]
	global_atomic_add_f32 v[166:167], v38, off
	s_mov_b64 exec, s[84:85]
.Lmg4_end:
	s_cmp_lt_u32 s33, 32
	s_cbranch_scc1 .Lcpy4_end
	v_lshrrev_b32_e32 v21, 6, v174
	v_and_b32_e32 v22, 63, v174
	v_lshlrev_b32_e32 v22, 4, v22
	v_readfirstlane_b32 s80, v21
	v_add_u32_e32 v23, 0x1000, v22
	v_readfirstlane_b32 s92, v235
	v_readfirstlane_b32 s93, v236
	v_readfirstlane_b32 s94, v237
	v_readfirstlane_b32 s95, v238
	v_readfirstlane_b32 s98, v239
	v_readfirstlane_b32 s99, v240
	s_add_i32 s80, s80, s33
	s_add_i32 s80, s80, 0x15570
	s_sub_i32 s100, s78, 4
	s_lshl_b32 s100, s100, 3

.LBB0_1543:
	s_or_b64 exec, exec, s[2:3]
	v_mov_b32_e32 v1, v174
	s_barrier
	v_lshrrev_b32_e32 v0, 6, v174
	v_and_b32_e32 v1, 63, v174
	v_lshlrev_b32_e32 v1, 4, v1
	v_readfirstlane_b32 s4, v0
	v_mov_b32_e32 v2, 0
	v_mov_b32_e32 v3, 0x358637bd
	s_add_i32 s4, s4, s33
	s_cmpk_lt_u32 s4, 0x4100
	s_cbranch_scc0 .Lfin_done
	global_load_dwordx4 v[100:103], v1, s[70:71]
	global_load_dwordx4 v[104:107], v1, s[70:71] offset:1024
	global_load_dwordx4 v[108:111], v1, s[70:71] offset:2048
	global_load_dwordx4 v[112:115], v1, s[70:71] offset:3072
	s_add_u32 s6, s74, 0x5000000
	s_addc_u32 s7, s75, 0
	s_add_u32 s8, s74, 0x12bc1800
	s_addc_u32 s9, s75, 0
	s_mov_b32 s5, 0x800000
.Lfin_loop:
	s_mul_i32 s10, s76, 0
	s_add_i32 s10, s10, s4
	s_cmpk_lt_u32 s10, 0x4100
	s_cbranch_scc0 .Lfin_ld0
	s_lshl_b32 s11, s10, 12
	s_add_u32 s12, s6, s11
	s_addc_u32 s13, s7, 0
	s_lshl_b32 s11, s10, 2
	s_add_u32 s14, s8, s11
	s_addc_u32 s15, s9, 0
	global_load_dword v24, v2, s[14:15]
	global_load_dwordx4 v[8:11], v1, s[12:13]
	global_load_dwordx4 v[12:15], v1, s[12:13] offset:1024
	global_load_dwordx4 v[16:19], v1, s[12:13] offset:2048
	global_load_dwordx4 v[20:23], v1, s[12:13] offset:3072
.Lfin_ld0:
	s_mul_i32 s10, s76, 1
	s_add_i32 s10, s10, s4
	s_cmpk_lt_u32 s10, 0x4100
	s_cbranch_scc0 .Lfin_ld1
	s_lshl_b32 s11, s10, 12
	s_add_u32 s12, s6, s11
	s_addc_u32 s13, s7, 0
	s_lshl_b32 s11, s10, 2
	s_add_u32 s14, s8, s11
	s_addc_u32 s15, s9, 0
	global_load_dword v44, v2, s[14:15]
	global_load_dwordx4 v[28:31], v1, s[12:13]
	global_load_dwordx4 v[32:35], v1, s[12:13] offset:1024
	global_load_dwordx4 v[36:39], v1, s[12:13] offset:2048
	global_load_dwordx4 v[40:43], v1, s[12:13] offset:3072
.Lfin_ld1:
	s_mul_i32 s10, s76, 2
	s_add_i32 s10, s10, s4
	s_cmpk_lt_u32 s10, 0x4100
	s_cbranch_scc0 .Lfin_ld2
	s_lshl_b32 s11, s10, 12
	s_add_u32 s12, s6, s11
	s_addc_u32 s13, s7, 0
	s_lshl_b32 s11, s10, 2
	s_add_u32 s14, s8, s11
	s_addc_u32 s15, s9, 0
	global_load_dword v64, v2, s[14:15]
	global_load_dwordx4 v[48:51], v1, s[12:13]
	global_load_dwordx4 v[52:55], v1, s[12:13] offset:1024
	global_load_dwordx4 v[56:59], v1, s[12:13] offset:2048
	global_load_dwordx4 v[60:63], v1, s[12:13] offset:3072
.Lfin_ld2:
	s_mul_i32 s10, s76, 3
	s_add_i32 s10, s10, s4
	s_cmpk_lt_u32 s10, 0x4100
	s_cbranch_scc0 .Lfin_ld3
	s_lshl_b32 s11, s10, 12
	s_add_u32 s12, s6, s11
	s_addc_u32 s13, s7, 0
	s_lshl_b32 s11, s10, 2
	s_add_u32 s14, s8, s11
	s_addc_u32 s15, s9, 0
	global_load_dword v84, v2, s[14:15]
	global_load_dwordx4 v[68:71], v1, s[12:13]
	global_load_dwordx4 v[72:75], v1, s[12:13] offset:1024
	global_load_dwordx4 v[76:79], v1, s[12:13] offset:2048
	global_load_dwordx4 v[80:83], v1, s[12:13] offset:3072
.Lfin_ld3:
	s_waitcnt vmcnt(0)
	s_mul_i32 s10, s76, 0
	s_add_i32 s10, s10, s4
	s_cmpk_lt_u32 s10, 0x4100
	s_cbranch_scc0 .Lfin_st0
	s_lshl_b32 s11, s10, 12
	s_add_u32 s12, s72, s11
	s_addc_u32 s13, s73, 0
	v_fmamk_f32 v4, v24, 0x3a800000, v3
	v_mul_f32_e32 v6, 0x4b800000, v4
	v_cmp_gt_f32_e32 vcc, s5, v4
	s_nop 1
	v_cndmask_b32_e32 v4, v4, v6, vcc
	v_rsq_f32_e32 v4, v4
	s_nop 0
	v_mul_f32_e32 v6, 0x45800000, v4
	v_cndmask_b32_e32 v4, v4, v6, vcc
	v_mov_b32_e32 v5, 0
	v_pk_mul_f32 v[10:11], v[4:5], v[10:11] op_sel_hi:[0,1]
	v_pk_mul_f32 v[8:9], v[4:5], v[8:9] op_sel_hi:[0,1]
	v_pk_mul_f32 v[8:9], v[8:9], v[100:101]
	v_pk_mul_f32 v[10:11], v[10:11], v[102:103]
	global_store_dwordx4 v1, v[8:11], s[12:13]
	v_pk_mul_f32 v[14:15], v[4:5], v[14:15] op_sel_hi:[0,1]
	v_pk_mul_f32 v[12:13], v[4:5], v[12:13] op_sel_hi:[0,1]
	v_pk_mul_f32 v[12:13], v[12:13], v[104:105]
	v_pk_mul_f32 v[14:15], v[14:15], v[106:107]
	global_store_dwordx4 v1, v[12:15], s[12:13] offset:1024
	v_pk_mul_f32 v[18:19], v[4:5], v[18:19] op_sel_hi:[0,1]
	v_pk_mul_f32 v[16:17], v[4:5], v[16:17] op_sel_hi:[0,1]
	v_pk_mul_f32 v[16:17], v[16:17], v[108:109]
	v_pk_mul_f32 v[18:19], v[18:19], v[110:111]
	global_store_dwordx4 v1, v[16:19], s[12:13] offset:2048
	v_pk_mul_f32 v[22:23], v[4:5], v[22:23] op_sel_hi:[0,1]
	v_pk_mul_f32 v[20:21], v[4:5], v[20:21] op_sel_hi:[0,1]
	v_pk_mul_f32 v[20:21], v[20:21], v[112:113]
	v_pk_mul_f32 v[22:23], v[22:23], v[114:115]
	global_store_dwordx4 v1, v[20:23], s[12:13] offset:3072
.Lfin_st0:
	s_mul_i32 s10, s76, 1
	s_add_i32 s10, s10, s4
	s_cmpk_lt_u32 s10, 0x4100
	s_cbranch_scc0 .Lfin_st1
	s_lshl_b32 s11, s10, 12
	s_add_u32 s12, s72, s11
	s_addc_u32 s13, s73, 0
	v_fmamk_f32 v4, v44, 0x3a800000, v3
	v_mul_f32_e32 v6, 0x4b800000, v4
	v_cmp_gt_f32_e32 vcc, s5, v4
	s_nop 1
	v_cndmask_b32_e32 v4, v4, v6, vcc
	v_rsq_f32_e32 v4, v4
	s_nop 0
	v_mul_f32_e32 v6, 0x45800000, v4
	v_cndmask_b32_e32 v4, v4, v6, vcc
	v_mov_b32_e32 v5, 0
	v_pk_mul_f32 v[30:31], v[4:5], v[30:31] op_sel_hi:[0,1]
	v_pk_mul_f32 v[28:29], v[4:5], v[28:29] op_sel_hi:[0,1]
	v_pk_mul_f32 v[28:29], v[28:29], v[100:101]
	v_pk_mul_f32 v[30:31], v[30:31], v[102:103]
	global_store_dwordx4 v1, v[28:31], s[12:13]
	v_pk_mul_f32 v[34:35], v[4:5], v[34:35] op_sel_hi:[0,1]
	v_pk_mul_f32 v[32:33], v[4:5], v[32:33] op_sel_hi:[0,1]
	v_pk_mul_f32 v[32:33], v[32:33], v[104:105]
	v_pk_mul_f32 v[34:35], v[34:35], v[106:107]
	global_store_dwordx4 v1, v[32:35], s[12:13] offset:1024
	v_pk_mul_f32 v[38:39], v[4:5], v[38:39] op_sel_hi:[0,1]
	v_pk_mul_f32 v[36:37], v[4:5], v[36:37] op_sel_hi:[0,1]
	v_pk_mul_f32 v[36:37], v[36:37], v[108:109]
	v_pk_mul_f32 v[38:39], v[38:39], v[110:111]
	global_store_dwordx4 v1, v[36:39], s[12:13] offset:2048
	v_pk_mul_f32 v[42:43], v[4:5], v[42:43] op_sel_hi:[0,1]
	v_pk_mul_f32 v[40:41], v[4:5], v[40:41] op_sel_hi:[0,1]
	v_pk_mul_f32 v[40:41], v[40:41], v[112:113]
	v_pk_mul_f32 v[42:43], v[42:43], v[114:115]
	global_store_dwordx4 v1, v[40:43], s[12:13] offset:3072
.Lfin_st1:
	s_mul_i32 s10, s76, 2
	s_add_i32 s10, s10, s4
	s_cmpk_lt_u32 s10, 0x4100
	s_cbranch_scc0 .Lfin_st2
	s_lshl_b32 s11, s10, 12
	s_add_u32 s12, s72, s11
	s_addc_u32 s13, s73, 0
	v_fmamk_f32 v4, v64, 0x3a800000, v3
	v_mul_f32_e32 v6, 0x4b800000, v4
	v_cmp_gt_f32_e32 vcc, s5, v4
	s_nop 1
	v_cndmask_b32_e32 v4, v4, v6, vcc
	v_rsq_f32_e32 v4, v4
	s_nop 0
	v_mul_f32_e32 v6, 0x45800000, v4
	v_cndmask_b32_e32 v4, v4, v6, vcc
	v_mov_b32_e32 v5, 0
	v_pk_mul_f32 v[50:51], v[4:5], v[50:51] op_sel_hi:[0,1]
	v_pk_mul_f32 v[48:49], v[4:5], v[48:49] op_sel_hi:[0,1]
	v_pk_mul_f32 v[48:49], v[48:49], v[100:101]
	v_pk_mul_f32 v[50:51], v[50:51], v[102:103]
	global_store_dwordx4 v1, v[48:51], s[12:13]
	v_pk_mul_f32 v[54:55], v[4:5], v[54:55] op_sel_hi:[0,1]
	v_pk_mul_f32 v[52:53], v[4:5], v[52:53] op_sel_hi:[0,1]
	v_pk_mul_f32 v[52:53], v[52:53], v[104:105]
	v_pk_mul_f32 v[54:55], v[54:55], v[106:107]
	global_store_dwordx4 v1, v[52:55], s[12:13] offset:1024
	v_pk_mul_f32 v[58:59], v[4:5], v[58:59] op_sel_hi:[0,1]
	v_pk_mul_f32 v[56:57], v[4:5], v[56:57] op_sel_hi:[0,1]
	v_pk_mul_f32 v[56:57], v[56:57], v[108:109]
	v_pk_mul_f32 v[58:59], v[58:59], v[110:111]
	global_store_dwordx4 v1, v[56:59], s[12:13] offset:2048
	v_pk_mul_f32 v[62:63], v[4:5], v[62:63] op_sel_hi:[0,1]
	v_pk_mul_f32 v[60:61], v[4:5], v[60:61] op_sel_hi:[0,1]
	v_pk_mul_f32 v[60:61], v[60:61], v[112:113]
	v_pk_mul_f32 v[62:63], v[62:63], v[114:115]
	global_store_dwordx4 v1, v[60:63], s[12:13] offset:3072
.Lfin_st2:
	s_mul_i32 s10, s76, 3
	s_add_i32 s10, s10, s4
	s_cmpk_lt_u32 s10, 0x4100
	s_cbranch_scc0 .Lfin_st3
	s_lshl_b32 s11, s10, 12
	s_add_u32 s12, s72, s11
	s_addc_u32 s13, s73, 0
	v_fmamk_f32 v4, v84, 0x3a800000, v3
	v_mul_f32_e32 v6, 0x4b800000, v4
	v_cmp_gt_f32_e32 vcc, s5, v4
	s_nop 1
	v_cndmask_b32_e32 v4, v4, v6, vcc
	v_rsq_f32_e32 v4, v4
	s_nop 0
	v_mul_f32_e32 v6, 0x45800000, v4
	v_cndmask_b32_e32 v4, v4, v6, vcc
	v_mov_b32_e32 v5, 0
	v_pk_mul_f32 v[70:71], v[4:5], v[70:71] op_sel_hi:[0,1]
	v_pk_mul_f32 v[68:69], v[4:5], v[68:69] op_sel_hi:[0,1]
	v_pk_mul_f32 v[68:69], v[68:69], v[100:101]
	v_pk_mul_f32 v[70:71], v[70:71], v[102:103]
	global_store_dwordx4 v1, v[68:71], s[12:13]
	v_pk_mul_f32 v[74:75], v[4:5], v[74:75] op_sel_hi:[0,1]
	v_pk_mul_f32 v[72:73], v[4:5], v[72:73] op_sel_hi:[0,1]
	v_pk_mul_f32 v[72:73], v[72:73], v[104:105]
	v_pk_mul_f32 v[74:75], v[74:75], v[106:107]
	global_store_dwordx4 v1, v[72:75], s[12:13] offset:1024
	v_pk_mul_f32 v[78:79], v[4:5], v[78:79] op_sel_hi:[0,1]
	v_pk_mul_f32 v[76:77], v[4:5], v[76:77] op_sel_hi:[0,1]
	v_pk_mul_f32 v[76:77], v[76:77], v[108:109]
	v_pk_mul_f32 v[78:79], v[78:79], v[110:111]
	global_store_dwordx4 v1, v[76:79], s[12:13] offset:2048
	v_pk_mul_f32 v[82:83], v[4:5], v[82:83] op_sel_hi:[0,1]
	v_pk_mul_f32 v[80:81], v[4:5], v[80:81] op_sel_hi:[0,1]
	v_pk_mul_f32 v[80:81], v[80:81], v[112:113]
	v_pk_mul_f32 v[82:83], v[82:83], v[114:115]
	global_store_dwordx4 v1, v[80:83], s[12:13] offset:3072
.Lfin_st3:
	s_lshl_b32 s10, s76, 2
	s_add_i32 s4, s4, s10
	s_cmpk_lt_u32 s4, 0x4100
	s_cbranch_scc1 .Lfin_loop
.Lfin_done:
.LBB0_1548:
	s_endpgm
